# speedup vs baseline: 1.0231x; 1.0172x over previous
; template <int MODE>
; DEV void gemm_phase(const bf16_t* __restrict__ A, const bf16_t* __restrict__ Bt, int M, int N, int K, bf16_t* __restrict__ Out, int ldo,
;                     const float* __restrict__ rstd, const float* __restrict__ rope) {
;     ...
;       const bool ropet = (MODE == G_INPROJ) && (pn >= 12 && pn < 20) && ((wc & 1) == 0);
; #pragma unroll
;       for (int ai = 0; ai < 2; ++ai)
; #pragma unroll
;         for (int m = 0; m < 4; ++m) {
;           const int row = brow + ai * HALF + wr * 64 + m * 16 + fr;
;           float rs = 1.f; if constexpr (MODE == G_INPROJ) rs = rstd[row];
; #pragma unroll
;           for (int bj = 0; bj < 2; ++bj) {
;             f32x4 v0 = acc[ai][bj][m][0], v1 = acc[ai][bj][m][1];
;             if constexpr (MODE == G_INPROJ) {
;               if (ropet) {
;                 const f32x4 c0 = *reinterpret_cast<const f32x4*>(rope + (size_t)row * 16), c1 = *reinterpret_cast<const f32x4*>(rope + (size_t)row * 16 + 4);
;                 const f32x4 s0 = *reinterpret_cast<const f32x4*>(rope + (size_t)row * 16 + 8), s1 = *reinterpret_cast<const f32x4*>(rope + (size_t)row * 16 + 12);
; #pragma unroll
;                 for (int j = 0; j < 4; ++j) { const float p0_ = __shfl_xor(v0[j], 16), p1_ = __shfl_xor(v1[j], 16);
;                   if (fq < 2) { v0[j] = (fq == 0) ? (v0[j] * c0[j] - p0_ * s0[j]) : (v0[j] * c0[j] + p0_ * s0[j]);
;                                 v1[j] = (fq == 0) ? (v1[j] * c1[j] - p1_ * s1[j]) : (v1[j] * c1[j] + p1_ * s1[j]); } }
.LBB0_131:
	v_lshl_add_u32 v164, s41, 8, v170
	v_ashrrev_i32_e32 v165, 31, v164
	v_lshl_add_u64 v[128:129], v[164:165], 2, s[68:69]
	global_load_dword v194, v[128:129], off
	global_load_dword v196, v[128:129], off offset:64
	global_load_dword v198, v[128:129], off offset:128
	global_load_dword v200, v[128:129], off offset:192
	global_load_dword v202, v[128:129], off offset:512
	global_load_dword v204, v[128:129], off offset:576
	global_load_dword v206, v[128:129], off offset:640
	global_load_dword v208, v[128:129], off offset:704
	s_add_i32 s8, s40, -12
	s_cmp_lt_u32 s8, 8
	s_cselect_b64 s[8:9], -1, 0
	s_and_b64 s[26:27], s[8:9], s[14:15]
	v_lshlrev_b64 v[128:129], 6, v[164:165]
	v_lshl_add_u64 v[168:169], s[72:73], 0, v[128:129]
	s_and_b64 vcc, exec, s[26:27]
	s_cbranch_vccz .LBB0_141
	global_load_dwordx4 v[132:135], v[168:169], off offset:48
	global_load_dwordx4 v[144:147], v[168:169], off offset:32
	global_load_dwordx4 v[128:131], v[168:169], off offset:16
	global_load_dwordx4 v[136:139], v[168:169], off
	v_and_b32_e32 v141, 64, v211
	v_xor_b32_e32 v140, 16, v211
	v_add_u32_e32 v141, 64, v141
	v_cmp_lt_i32_e32 vcc, v140, v141
	v_mov_b64_e32 v[150:151], v[122:123]
	v_mov_b64_e32 v[148:149], v[120:121]
	v_cndmask_b32_e32 v140, v211, v140, vcc
	v_lshlrev_b32_e32 v165, 2, v140
	ds_bpermute_b32 v173, v165, v124
	ds_bpermute_b32 v167, v165, v120
	v_mov_b64_e32 v[142:143], v[126:127]
	v_mov_b64_e32 v[140:141], v[124:125]
	s_and_saveexec_b64 s[8:9], s[4:5]
	s_cbranch_execz .LBB0_134
	s_waitcnt vmcnt(0) lgkmcnt(0)
	v_mul_f32_e32 v140, v144, v173
	v_cndmask_b32_e64 v144, v140, -v140, s[6:7]
	v_mov_b64_e32 v[142:143], v[126:127]
	v_fmac_f32_e32 v144, v124, v136
	v_mov_b64_e32 v[140:141], v[124:125]
	v_mul_f32_e32 v124, v132, v167
	v_cndmask_b32_e64 v124, v124, -v124, s[6:7]
	v_mov_b64_e32 v[150:151], v[122:123]
	v_fmac_f32_e32 v124, v120, v128
	v_mov_b64_e32 v[148:149], v[120:121]
	v_mov_b32_e32 v140, v144
	v_mov_b32_e32 v148, v124

; DEV unsigned cvtpk(float lo, float hi) { f32x2_t v = {lo, hi}; bf16x2_t b = __builtin_convertvector(v, bf16x2_t); return __builtin_bit_cast(unsigned, b); }
; template <int MODE>
; DEV void gemm_phase(const bf16_t* __restrict__ A, const bf16_t* __restrict__ Bt, int M, int N, int K, bf16_t* __restrict__ Out, int ldo,
;                     const float* __restrict__ rstd, const float* __restrict__ rope) {
;     ...
;           const int row = brow + ai * HALF + wr * 64 + m * 16 + fr;
;           float rs = 1.f; if constexpr (MODE == G_INPROJ) rs = rstd[row];
; #pragma unroll
;           for (int bj = 0; bj < 2; ++bj) {
;             f32x4 v0 = acc[ai][bj][m][0], v1 = acc[ai][bj][m][1];
;             if constexpr (MODE == G_INPROJ) {
;               if (ropet) {
;                 const f32x4 c0 = *reinterpret_cast<const f32x4*>(rope + (size_t)row * 16), c1 = *reinterpret_cast<const f32x4*>(rope + (size_t)row * 16 + 4);
;                 const f32x4 s0 = *reinterpret_cast<const f32x4*>(rope + (size_t)row * 16 + 8), s1 = *reinterpret_cast<const f32x4*>(rope + (size_t)row * 16 + 12);
; #pragma unroll
;                 for (int j = 0; j < 4; ++j) { const float p0_ = __shfl_xor(v0[j], 16), p1_ = __shfl_xor(v1[j], 16);
;                   if (fq < 2) { v0[j] = (fq == 0) ? (v0[j] * c0[j] - p0_ * s0[j]) : (v0[j] * c0[j] + p0_ * s0[j]);
;                                 v1[j] = (fq == 0) ? (v1[j] * c1[j] - p1_ * s1[j]) : (v1[j] * c1[j] + p1_ * s1[j]); } }
;               }
;             }
;             u32x4 w = {cvtpk(v0[0] * rs, v0[1] * rs), cvtpk(v0[2] * rs, v0[3] * rs), cvtpk(v1[0] * rs, v1[1] * rs), cvtpk(v1[2] * rs, v1[3] * rs)};
;             *reinterpret_cast<u32x4*>(Out + (size_t)row * ldo + bcol + bj * HALF + wc * 32 + fq * 8) = w; } }
.LBB0_141:
	s_lshl_b32 s8, s40, 8
	s_ashr_i32 s9, s8, 31
	s_waitcnt vmcnt(0)
	v_pk_mul_f32 v[124:125], v[194:195], v[124:125] op_sel_hi:[0,1]
	v_pk_mul_f32 v[126:127], v[194:195], v[126:127] op_sel_hi:[0,1]
	v_pk_mul_f32 v[120:121], v[194:195], v[120:121] op_sel_hi:[0,1]
	v_lshl_add_u64 v[144:145], s[8:9], 1, v[158:159]
	v_cvt_pk_bf16_f32 v124, v124, v125
	v_cvt_pk_bf16_f32 v125, v126, v127
	v_cvt_pk_bf16_f32 v126, v120, v121
	v_pk_mul_f32 v[120:121], v[194:195], v[122:123] op_sel_hi:[0,1]
	v_mad_i64_i32 v[146:147], s[8:9], v164, s85, v[144:145]
	v_cvt_pk_bf16_f32 v127, v120, v121
	v_cndmask_b32_e64 v120, 0, 1, s[26:27]
	v_cmp_ne_u32_e64 s[8:9], 1, v120
	s_andn2_b64 vcc, exec, s[26:27]
	global_store_dwordx4 v[146:147], v[124:127], off
	s_cbranch_vccnz .LBB0_151
	global_load_dwordx4 v[124:127], v[168:169], off offset:48
	global_load_dwordx4 v[136:139], v[168:169], off offset:32
	global_load_dwordx4 v[120:123], v[168:169], off offset:16
	global_load_dwordx4 v[128:131], v[168:169], off
	v_and_b32_e32 v133, 64, v211
	v_xor_b32_e32 v132, 16, v211
	v_add_u32_e32 v133, 64, v133
	v_cmp_lt_i32_e32 vcc, v132, v133
	v_mov_b64_e32 v[142:143], v[114:115]
	v_mov_b64_e32 v[140:141], v[112:113]
	v_cndmask_b32_e32 v132, v211, v132, vcc
	v_lshlrev_b32_e32 v148, 2, v132
	ds_bpermute_b32 v150, v148, v116
	ds_bpermute_b32 v149, v148, v112
	v_mov_b64_e32 v[134:135], v[118:119]
	v_mov_b64_e32 v[132:133], v[116:117]
	s_and_saveexec_b64 s[26:27], s[4:5]
	s_cbranch_execz .LBB0_144
	s_waitcnt vmcnt(2) lgkmcnt(1)
	v_mul_f32_e32 v132, v136, v150
	v_cndmask_b32_e64 v136, v132, -v132, s[6:7]
	v_mov_b64_e32 v[134:135], v[118:119]
	s_waitcnt vmcnt(0)
	v_fmac_f32_e32 v136, v116, v128
	v_mov_b64_e32 v[132:133], v[116:117]
	s_waitcnt lgkmcnt(0)
	v_mul_f32_e32 v116, v124, v149
	v_cndmask_b32_e64 v116, v116, -v116, s[6:7]
	v_mov_b64_e32 v[142:143], v[114:115]
	v_fmac_f32_e32 v116, v112, v120
	v_mov_b64_e32 v[140:141], v[112:113]
	v_mov_b32_e32 v132, v136
	v_mov_b32_e32 v140, v116

; DEV unsigned cvtpk(float lo, float hi) { f32x2_t v = {lo, hi}; bf16x2_t b = __builtin_convertvector(v, bf16x2_t); return __builtin_bit_cast(unsigned, b); }
; template <int MODE>
; DEV void gemm_phase(const bf16_t* __restrict__ A, const bf16_t* __restrict__ Bt, int M, int N, int K, bf16_t* __restrict__ Out, int ldo,
;                     const float* __restrict__ rstd, const float* __restrict__ rope) {
;     ...
;           const int row = brow + ai * HALF + wr * 64 + m * 16 + fr;
;           float rs = 1.f; if constexpr (MODE == G_INPROJ) rs = rstd[row];
; #pragma unroll
;           for (int bj = 0; bj < 2; ++bj) {
;             f32x4 v0 = acc[ai][bj][m][0], v1 = acc[ai][bj][m][1];
;             if constexpr (MODE == G_INPROJ) {
;               if (ropet) {
;                 const f32x4 c0 = *reinterpret_cast<const f32x4*>(rope + (size_t)row * 16), c1 = *reinterpret_cast<const f32x4*>(rope + (size_t)row * 16 + 4);
;                 const f32x4 s0 = *reinterpret_cast<const f32x4*>(rope + (size_t)row * 16 + 8), s1 = *reinterpret_cast<const f32x4*>(rope + (size_t)row * 16 + 12);
; #pragma unroll
;                 for (int j = 0; j < 4; ++j) { const float p0_ = __shfl_xor(v0[j], 16), p1_ = __shfl_xor(v1[j], 16);
;                   if (fq < 2) { v0[j] = (fq == 0) ? (v0[j] * c0[j] - p0_ * s0[j]) : (v0[j] * c0[j] + p0_ * s0[j]);
;                                 v1[j] = (fq == 0) ? (v1[j] * c1[j] - p1_ * s1[j]) : (v1[j] * c1[j] + p1_ * s1[j]); } }
;               }
;             }
;             u32x4 w = {cvtpk(v0[0] * rs, v0[1] * rs), cvtpk(v0[2] * rs, v0[3] * rs), cvtpk(v1[0] * rs, v1[1] * rs), cvtpk(v1[2] * rs, v1[3] * rs)};
;             *reinterpret_cast<u32x4*>(Out + (size_t)row * ldo + bcol + bj * HALF + wc * 32 + fq * 8) = w; } }
.LBB0_151:
	v_mov_b32_e32 v195, v194
	v_pk_mul_f32 v[116:117], v[194:195], v[116:117]
	v_pk_mul_f32 v[118:119], v[194:195], v[118:119]
	v_pk_mul_f32 v[112:113], v[194:195], v[112:113]
	v_or_b32_e32 v138, 16, v164
	v_cvt_pk_bf16_f32 v116, v116, v117
	v_cvt_pk_bf16_f32 v117, v118, v119
	v_cvt_pk_bf16_f32 v118, v112, v113
	v_pk_mul_f32 v[112:113], v[194:195], v[114:115]
	v_ashrrev_i32_e32 v139, 31, v138
	v_cvt_pk_bf16_f32 v119, v112, v113
	v_lshl_add_u64 v[112:113], v[138:139], 2, s[68:69]
	v_lshlrev_b64 v[112:113], 6, v[138:139]
	v_lshl_add_u64 v[140:141], s[72:73], 0, v[112:113]
	s_and_b64 vcc, exec, s[8:9]
	global_store_dwordx4 v[146:147], v[116:119], off offset:256
	s_cbranch_vccnz .LBB0_161
	global_load_dwordx4 v[116:119], v[140:141], off offset:48
	global_load_dwordx4 v[128:131], v[140:141], off offset:32
	global_load_dwordx4 v[112:115], v[140:141], off offset:16
	global_load_dwordx4 v[120:123], v[140:141], off
	v_and_b32_e32 v125, 64, v211
	v_xor_b32_e32 v124, 16, v211
	v_add_u32_e32 v125, 64, v125
	v_cmp_lt_i32_e32 vcc, v124, v125
	v_mov_b64_e32 v[134:135], v[106:107]
	v_mov_b64_e32 v[132:133], v[104:105]
	v_cndmask_b32_e32 v124, v211, v124, vcc
	v_lshlrev_b32_e32 v137, 2, v124
	ds_bpermute_b32 v142, v137, v108
	ds_bpermute_b32 v139, v137, v104
	v_mov_b64_e32 v[126:127], v[110:111]
	v_mov_b64_e32 v[124:125], v[108:109]
	s_and_saveexec_b64 s[26:27], s[4:5]
	s_cbranch_execz .LBB0_154
	s_waitcnt vmcnt(2) lgkmcnt(1)
	v_mul_f32_e32 v124, v128, v142
	v_cndmask_b32_e64 v128, v124, -v124, s[6:7]
	v_mov_b64_e32 v[126:127], v[110:111]
	s_waitcnt vmcnt(0)
	v_fmac_f32_e32 v128, v108, v120
	v_mov_b64_e32 v[124:125], v[108:109]
	s_waitcnt lgkmcnt(0)
	v_mul_f32_e32 v108, v116, v139
	v_cndmask_b32_e64 v108, v108, -v108, s[6:7]
	v_mov_b64_e32 v[134:135], v[106:107]
	v_fmac_f32_e32 v108, v104, v112
	v_mov_b64_e32 v[132:133], v[104:105]
	v_mov_b32_e32 v124, v128
	v_mov_b32_e32 v132, v108

; DEV unsigned cvtpk(float lo, float hi) { f32x2_t v = {lo, hi}; bf16x2_t b = __builtin_convertvector(v, bf16x2_t); return __builtin_bit_cast(unsigned, b); }
; template <int MODE>
; DEV void gemm_phase(const bf16_t* __restrict__ A, const bf16_t* __restrict__ Bt, int M, int N, int K, bf16_t* __restrict__ Out, int ldo,
;                     const float* __restrict__ rstd, const float* __restrict__ rope) {
;     ...
;           const int row = brow + ai * HALF + wr * 64 + m * 16 + fr;
;           float rs = 1.f; if constexpr (MODE == G_INPROJ) rs = rstd[row];
; #pragma unroll
;           for (int bj = 0; bj < 2; ++bj) {
;             f32x4 v0 = acc[ai][bj][m][0], v1 = acc[ai][bj][m][1];
;             if constexpr (MODE == G_INPROJ) {
;               if (ropet) {
;                 const f32x4 c0 = *reinterpret_cast<const f32x4*>(rope + (size_t)row * 16), c1 = *reinterpret_cast<const f32x4*>(rope + (size_t)row * 16 + 4);
;                 const f32x4 s0 = *reinterpret_cast<const f32x4*>(rope + (size_t)row * 16 + 8), s1 = *reinterpret_cast<const f32x4*>(rope + (size_t)row * 16 + 12);
; #pragma unroll
;                 for (int j = 0; j < 4; ++j) { const float p0_ = __shfl_xor(v0[j], 16), p1_ = __shfl_xor(v1[j], 16);
;                   if (fq < 2) { v0[j] = (fq == 0) ? (v0[j] * c0[j] - p0_ * s0[j]) : (v0[j] * c0[j] + p0_ * s0[j]);
;                                 v1[j] = (fq == 0) ? (v1[j] * c1[j] - p1_ * s1[j]) : (v1[j] * c1[j] + p1_ * s1[j]); } }
;               }
;             }
;             u32x4 w = {cvtpk(v0[0] * rs, v0[1] * rs), cvtpk(v0[2] * rs, v0[3] * rs), cvtpk(v1[0] * rs, v1[1] * rs), cvtpk(v1[2] * rs, v1[3] * rs)};
;             *reinterpret_cast<u32x4*>(Out + (size_t)row * ldo + bcol + bj * HALF + wc * 32 + fq * 8) = w; } }
.LBB0_161:
	v_pk_mul_f32 v[108:109], v[196:197], v[108:109] op_sel_hi:[0,1]
	v_pk_mul_f32 v[110:111], v[196:197], v[110:111] op_sel_hi:[0,1]
	v_pk_mul_f32 v[104:105], v[196:197], v[104:105] op_sel_hi:[0,1]
	v_cvt_pk_bf16_f32 v108, v108, v109
	v_cvt_pk_bf16_f32 v109, v110, v111
	v_cvt_pk_bf16_f32 v110, v104, v105
	v_pk_mul_f32 v[104:105], v[196:197], v[106:107] op_sel_hi:[0,1]
	v_mad_i64_i32 v[128:129], s[26:27], v138, s85, v[144:145]
	v_cvt_pk_bf16_f32 v111, v104, v105
	s_and_b64 vcc, exec, s[8:9]
	global_store_dwordx4 v[128:129], v[108:111], off
	s_cbranch_vccnz .LBB0_171
	global_load_dwordx4 v[108:111], v[140:141], off offset:48
	global_load_dwordx4 v[120:123], v[140:141], off offset:32
	global_load_dwordx4 v[104:107], v[140:141], off offset:16
	global_load_dwordx4 v[112:115], v[140:141], off
	v_and_b32_e32 v117, 64, v211
	v_xor_b32_e32 v116, 16, v211
	v_add_u32_e32 v117, 64, v117
	v_cmp_lt_i32_e32 vcc, v116, v117
	v_mov_b64_e32 v[126:127], v[98:99]
	v_mov_b64_e32 v[124:125], v[96:97]
	v_cndmask_b32_e32 v116, v211, v116, vcc
	v_lshlrev_b32_e32 v130, 2, v116
	ds_bpermute_b32 v132, v130, v100
	ds_bpermute_b32 v131, v130, v96
	v_mov_b64_e32 v[118:119], v[102:103]
	v_mov_b64_e32 v[116:117], v[100:101]
	s_and_saveexec_b64 s[26:27], s[4:5]
	s_cbranch_execz .LBB0_164
	s_waitcnt vmcnt(2) lgkmcnt(1)
	v_mul_f32_e32 v116, v120, v132
	v_cndmask_b32_e64 v120, v116, -v116, s[6:7]
	v_mov_b64_e32 v[118:119], v[102:103]
	s_waitcnt vmcnt(0)
	v_fmac_f32_e32 v120, v100, v112
	v_mov_b64_e32 v[116:117], v[100:101]
	s_waitcnt lgkmcnt(0)
	v_mul_f32_e32 v100, v108, v131
	v_cndmask_b32_e64 v100, v100, -v100, s[6:7]
	v_mov_b64_e32 v[126:127], v[98:99]
	v_fmac_f32_e32 v100, v96, v104
	v_mov_b64_e32 v[124:125], v[96:97]
	v_mov_b32_e32 v116, v120
	v_mov_b32_e32 v124, v100

; DEV unsigned cvtpk(float lo, float hi) { f32x2_t v = {lo, hi}; bf16x2_t b = __builtin_convertvector(v, bf16x2_t); return __builtin_bit_cast(unsigned, b); }
; template <int MODE>
; DEV void gemm_phase(const bf16_t* __restrict__ A, const bf16_t* __restrict__ Bt, int M, int N, int K, bf16_t* __restrict__ Out, int ldo,
;                     const float* __restrict__ rstd, const float* __restrict__ rope) {
;     ...
;           const int row = brow + ai * HALF + wr * 64 + m * 16 + fr;
;           float rs = 1.f; if constexpr (MODE == G_INPROJ) rs = rstd[row];
; #pragma unroll
;           for (int bj = 0; bj < 2; ++bj) {
;             f32x4 v0 = acc[ai][bj][m][0], v1 = acc[ai][bj][m][1];
;             if constexpr (MODE == G_INPROJ) {
;               if (ropet) {
;                 const f32x4 c0 = *reinterpret_cast<const f32x4*>(rope + (size_t)row * 16), c1 = *reinterpret_cast<const f32x4*>(rope + (size_t)row * 16 + 4);
;                 const f32x4 s0 = *reinterpret_cast<const f32x4*>(rope + (size_t)row * 16 + 8), s1 = *reinterpret_cast<const f32x4*>(rope + (size_t)row * 16 + 12);
; #pragma unroll
;                 for (int j = 0; j < 4; ++j) { const float p0_ = __shfl_xor(v0[j], 16), p1_ = __shfl_xor(v1[j], 16);
;                   if (fq < 2) { v0[j] = (fq == 0) ? (v0[j] * c0[j] - p0_ * s0[j]) : (v0[j] * c0[j] + p0_ * s0[j]);
;                                 v1[j] = (fq == 0) ? (v1[j] * c1[j] - p1_ * s1[j]) : (v1[j] * c1[j] + p1_ * s1[j]); } }
;               }
;             }
;             u32x4 w = {cvtpk(v0[0] * rs, v0[1] * rs), cvtpk(v0[2] * rs, v0[3] * rs), cvtpk(v1[0] * rs, v1[1] * rs), cvtpk(v1[2] * rs, v1[3] * rs)};
;             *reinterpret_cast<u32x4*>(Out + (size_t)row * ldo + bcol + bj * HALF + wc * 32 + fq * 8) = w; } }
.LBB0_171:
	v_mov_b32_e32 v197, v196
	v_pk_mul_f32 v[100:101], v[196:197], v[100:101]
	v_pk_mul_f32 v[102:103], v[196:197], v[102:103]
	v_pk_mul_f32 v[96:97], v[196:197], v[96:97]
	v_or_b32_e32 v122, 32, v164
	v_cvt_pk_bf16_f32 v100, v100, v101
	v_cvt_pk_bf16_f32 v101, v102, v103
	v_cvt_pk_bf16_f32 v102, v96, v97
	v_pk_mul_f32 v[96:97], v[196:197], v[98:99]
	v_ashrrev_i32_e32 v123, 31, v122
	v_cvt_pk_bf16_f32 v103, v96, v97
	v_lshl_add_u64 v[96:97], v[122:123], 2, s[68:69]
	v_lshlrev_b64 v[96:97], 6, v[122:123]
	v_lshl_add_u64 v[124:125], s[72:73], 0, v[96:97]
	s_and_b64 vcc, exec, s[8:9]
	global_store_dwordx4 v[128:129], v[100:103], off offset:256
	s_cbranch_vccnz .LBB0_181
	global_load_dwordx4 v[100:103], v[124:125], off offset:48
	global_load_dwordx4 v[112:115], v[124:125], off offset:32
	global_load_dwordx4 v[96:99], v[124:125], off offset:16
	global_load_dwordx4 v[104:107], v[124:125], off
	v_and_b32_e32 v109, 64, v211
	v_xor_b32_e32 v108, 16, v211
	v_add_u32_e32 v109, 64, v109
	v_cmp_lt_i32_e32 vcc, v108, v109
	v_mov_b64_e32 v[118:119], v[90:91]
	v_mov_b64_e32 v[116:117], v[88:89]
	v_cndmask_b32_e32 v108, v211, v108, vcc
	v_lshlrev_b32_e32 v121, 2, v108
	ds_bpermute_b32 v126, v121, v92
	ds_bpermute_b32 v123, v121, v88
	v_mov_b64_e32 v[110:111], v[94:95]
	v_mov_b64_e32 v[108:109], v[92:93]
	s_and_saveexec_b64 s[26:27], s[4:5]
	s_cbranch_execz .LBB0_174
	s_waitcnt vmcnt(2) lgkmcnt(1)
	v_mul_f32_e32 v108, v112, v126
	v_cndmask_b32_e64 v112, v108, -v108, s[6:7]
	v_mov_b64_e32 v[110:111], v[94:95]
	s_waitcnt vmcnt(0)
	v_fmac_f32_e32 v112, v92, v104
	v_mov_b64_e32 v[108:109], v[92:93]
	s_waitcnt lgkmcnt(0)
	v_mul_f32_e32 v92, v100, v123
	v_cndmask_b32_e64 v92, v92, -v92, s[6:7]
	v_mov_b64_e32 v[118:119], v[90:91]
	v_fmac_f32_e32 v92, v88, v96
	v_mov_b64_e32 v[116:117], v[88:89]
	v_mov_b32_e32 v108, v112
	v_mov_b32_e32 v116, v92

; DEV unsigned cvtpk(float lo, float hi) { f32x2_t v = {lo, hi}; bf16x2_t b = __builtin_convertvector(v, bf16x2_t); return __builtin_bit_cast(unsigned, b); }
; template <int MODE>
; DEV void gemm_phase(const bf16_t* __restrict__ A, const bf16_t* __restrict__ Bt, int M, int N, int K, bf16_t* __restrict__ Out, int ldo,
;                     const float* __restrict__ rstd, const float* __restrict__ rope) {
;     ...
;           const int row = brow + ai * HALF + wr * 64 + m * 16 + fr;
;           float rs = 1.f; if constexpr (MODE == G_INPROJ) rs = rstd[row];
; #pragma unroll
;           for (int bj = 0; bj < 2; ++bj) {
;             f32x4 v0 = acc[ai][bj][m][0], v1 = acc[ai][bj][m][1];
;             if constexpr (MODE == G_INPROJ) {
;               if (ropet) {
;                 const f32x4 c0 = *reinterpret_cast<const f32x4*>(rope + (size_t)row * 16), c1 = *reinterpret_cast<const f32x4*>(rope + (size_t)row * 16 + 4);
;                 const f32x4 s0 = *reinterpret_cast<const f32x4*>(rope + (size_t)row * 16 + 8), s1 = *reinterpret_cast<const f32x4*>(rope + (size_t)row * 16 + 12);
; #pragma unroll
;                 for (int j = 0; j < 4; ++j) { const float p0_ = __shfl_xor(v0[j], 16), p1_ = __shfl_xor(v1[j], 16);
;                   if (fq < 2) { v0[j] = (fq == 0) ? (v0[j] * c0[j] - p0_ * s0[j]) : (v0[j] * c0[j] + p0_ * s0[j]);
;                                 v1[j] = (fq == 0) ? (v1[j] * c1[j] - p1_ * s1[j]) : (v1[j] * c1[j] + p1_ * s1[j]); } }
;               }
;             }
;             u32x4 w = {cvtpk(v0[0] * rs, v0[1] * rs), cvtpk(v0[2] * rs, v0[3] * rs), cvtpk(v1[0] * rs, v1[1] * rs), cvtpk(v1[2] * rs, v1[3] * rs)};
;             *reinterpret_cast<u32x4*>(Out + (size_t)row * ldo + bcol + bj * HALF + wc * 32 + fq * 8) = w; } }
.LBB0_181:
	v_pk_mul_f32 v[92:93], v[198:199], v[92:93] op_sel_hi:[0,1]
	v_pk_mul_f32 v[94:95], v[198:199], v[94:95] op_sel_hi:[0,1]
	v_pk_mul_f32 v[88:89], v[198:199], v[88:89] op_sel_hi:[0,1]
	v_cvt_pk_bf16_f32 v92, v92, v93
	v_cvt_pk_bf16_f32 v93, v94, v95
	v_cvt_pk_bf16_f32 v94, v88, v89
	v_pk_mul_f32 v[88:89], v[198:199], v[90:91] op_sel_hi:[0,1]
	v_mad_i64_i32 v[112:113], s[26:27], v122, s85, v[144:145]
	v_cvt_pk_bf16_f32 v95, v88, v89
	s_and_b64 vcc, exec, s[8:9]
	global_store_dwordx4 v[112:113], v[92:95], off
	s_cbranch_vccnz .LBB0_191
	global_load_dwordx4 v[92:95], v[124:125], off offset:48
	global_load_dwordx4 v[104:107], v[124:125], off offset:32
	global_load_dwordx4 v[88:91], v[124:125], off offset:16
	global_load_dwordx4 v[96:99], v[124:125], off
	v_and_b32_e32 v101, 64, v211
	v_xor_b32_e32 v100, 16, v211
	v_add_u32_e32 v101, 64, v101
	v_cmp_lt_i32_e32 vcc, v100, v101
	v_mov_b64_e32 v[110:111], v[82:83]
	v_mov_b64_e32 v[108:109], v[80:81]
	v_cndmask_b32_e32 v100, v211, v100, vcc
	v_lshlrev_b32_e32 v114, 2, v100
	ds_bpermute_b32 v116, v114, v84
	ds_bpermute_b32 v115, v114, v80
	v_mov_b64_e32 v[102:103], v[86:87]
	v_mov_b64_e32 v[100:101], v[84:85]
	s_and_saveexec_b64 s[26:27], s[4:5]
	s_cbranch_execz .LBB0_184
	s_waitcnt vmcnt(2) lgkmcnt(1)
	v_mul_f32_e32 v100, v104, v116
	v_cndmask_b32_e64 v104, v100, -v100, s[6:7]
	v_mov_b64_e32 v[102:103], v[86:87]
	s_waitcnt vmcnt(0)
	v_fmac_f32_e32 v104, v84, v96
	v_mov_b64_e32 v[100:101], v[84:85]
	s_waitcnt lgkmcnt(0)
	v_mul_f32_e32 v84, v92, v115
	v_cndmask_b32_e64 v84, v84, -v84, s[6:7]
	v_mov_b64_e32 v[110:111], v[82:83]
	v_fmac_f32_e32 v84, v80, v88
	v_mov_b64_e32 v[108:109], v[80:81]
	v_mov_b32_e32 v100, v104
	v_mov_b32_e32 v108, v84

; DEV unsigned cvtpk(float lo, float hi) { f32x2_t v = {lo, hi}; bf16x2_t b = __builtin_convertvector(v, bf16x2_t); return __builtin_bit_cast(unsigned, b); }
; template <int MODE>
; DEV void gemm_phase(const bf16_t* __restrict__ A, const bf16_t* __restrict__ Bt, int M, int N, int K, bf16_t* __restrict__ Out, int ldo,
;                     const float* __restrict__ rstd, const float* __restrict__ rope) {
;     ...
;           const int row = brow + ai * HALF + wr * 64 + m * 16 + fr;
;           float rs = 1.f; if constexpr (MODE == G_INPROJ) rs = rstd[row];
; #pragma unroll
;           for (int bj = 0; bj < 2; ++bj) {
;             f32x4 v0 = acc[ai][bj][m][0], v1 = acc[ai][bj][m][1];
;             if constexpr (MODE == G_INPROJ) {
;               if (ropet) {
;                 const f32x4 c0 = *reinterpret_cast<const f32x4*>(rope + (size_t)row * 16), c1 = *reinterpret_cast<const f32x4*>(rope + (size_t)row * 16 + 4);
;                 const f32x4 s0 = *reinterpret_cast<const f32x4*>(rope + (size_t)row * 16 + 8), s1 = *reinterpret_cast<const f32x4*>(rope + (size_t)row * 16 + 12);
; #pragma unroll
;                 for (int j = 0; j < 4; ++j) { const float p0_ = __shfl_xor(v0[j], 16), p1_ = __shfl_xor(v1[j], 16);
;                   if (fq < 2) { v0[j] = (fq == 0) ? (v0[j] * c0[j] - p0_ * s0[j]) : (v0[j] * c0[j] + p0_ * s0[j]);
;                                 v1[j] = (fq == 0) ? (v1[j] * c1[j] - p1_ * s1[j]) : (v1[j] * c1[j] + p1_ * s1[j]); } }
;               }
;             }
;             u32x4 w = {cvtpk(v0[0] * rs, v0[1] * rs), cvtpk(v0[2] * rs, v0[3] * rs), cvtpk(v1[0] * rs, v1[1] * rs), cvtpk(v1[2] * rs, v1[3] * rs)};
;             *reinterpret_cast<u32x4*>(Out + (size_t)row * ldo + bcol + bj * HALF + wc * 32 + fq * 8) = w; } }
.LBB0_191:
	v_mov_b32_e32 v199, v198
	v_pk_mul_f32 v[84:85], v[198:199], v[84:85]
	v_pk_mul_f32 v[86:87], v[198:199], v[86:87]
	v_pk_mul_f32 v[80:81], v[198:199], v[80:81]
	v_or_b32_e32 v106, 48, v164
	v_cvt_pk_bf16_f32 v84, v84, v85
	v_cvt_pk_bf16_f32 v85, v86, v87
	v_cvt_pk_bf16_f32 v86, v80, v81
	v_pk_mul_f32 v[80:81], v[198:199], v[82:83]
	v_ashrrev_i32_e32 v107, 31, v106
	v_cvt_pk_bf16_f32 v87, v80, v81
	v_lshl_add_u64 v[80:81], v[106:107], 2, s[68:69]
	v_lshlrev_b64 v[80:81], 6, v[106:107]
	v_lshl_add_u64 v[108:109], s[72:73], 0, v[80:81]
	s_and_b64 vcc, exec, s[8:9]
	global_store_dwordx4 v[112:113], v[84:87], off offset:256
	s_cbranch_vccnz .LBB0_201
	global_load_dwordx4 v[84:87], v[108:109], off offset:48
	global_load_dwordx4 v[96:99], v[108:109], off offset:32
	global_load_dwordx4 v[80:83], v[108:109], off offset:16
	global_load_dwordx4 v[88:91], v[108:109], off
	v_and_b32_e32 v93, 64, v211
	v_xor_b32_e32 v92, 16, v211
	v_add_u32_e32 v93, 64, v93
	v_cmp_lt_i32_e32 vcc, v92, v93
	v_mov_b64_e32 v[102:103], v[74:75]
	v_mov_b64_e32 v[100:101], v[72:73]
	v_cndmask_b32_e32 v92, v211, v92, vcc
	v_lshlrev_b32_e32 v105, 2, v92
	ds_bpermute_b32 v110, v105, v76
	ds_bpermute_b32 v107, v105, v72
	v_mov_b64_e32 v[94:95], v[78:79]
	v_mov_b64_e32 v[92:93], v[76:77]
	s_and_saveexec_b64 s[26:27], s[4:5]
	s_cbranch_execz .LBB0_194
	s_waitcnt vmcnt(2) lgkmcnt(1)
	v_mul_f32_e32 v92, v96, v110
	v_cndmask_b32_e64 v96, v92, -v92, s[6:7]
	v_mov_b64_e32 v[94:95], v[78:79]
	s_waitcnt vmcnt(0)
	v_fmac_f32_e32 v96, v76, v88
	v_mov_b64_e32 v[92:93], v[76:77]
	s_waitcnt lgkmcnt(0)
	v_mul_f32_e32 v76, v84, v107
	v_cndmask_b32_e64 v76, v76, -v76, s[6:7]
	v_mov_b64_e32 v[102:103], v[74:75]
	v_fmac_f32_e32 v76, v72, v80
	v_mov_b64_e32 v[100:101], v[72:73]
	v_mov_b32_e32 v92, v96
	v_mov_b32_e32 v100, v76

; DEV unsigned cvtpk(float lo, float hi) { f32x2_t v = {lo, hi}; bf16x2_t b = __builtin_convertvector(v, bf16x2_t); return __builtin_bit_cast(unsigned, b); }
; template <int MODE>
; DEV void gemm_phase(const bf16_t* __restrict__ A, const bf16_t* __restrict__ Bt, int M, int N, int K, bf16_t* __restrict__ Out, int ldo,
;                     const float* __restrict__ rstd, const float* __restrict__ rope) {
;     ...
;           const int row = brow + ai * HALF + wr * 64 + m * 16 + fr;
;           float rs = 1.f; if constexpr (MODE == G_INPROJ) rs = rstd[row];
; #pragma unroll
;           for (int bj = 0; bj < 2; ++bj) {
;             f32x4 v0 = acc[ai][bj][m][0], v1 = acc[ai][bj][m][1];
;             if constexpr (MODE == G_INPROJ) {
;               if (ropet) {
;                 const f32x4 c0 = *reinterpret_cast<const f32x4*>(rope + (size_t)row * 16), c1 = *reinterpret_cast<const f32x4*>(rope + (size_t)row * 16 + 4);
;                 const f32x4 s0 = *reinterpret_cast<const f32x4*>(rope + (size_t)row * 16 + 8), s1 = *reinterpret_cast<const f32x4*>(rope + (size_t)row * 16 + 12);
; #pragma unroll
;                 for (int j = 0; j < 4; ++j) { const float p0_ = __shfl_xor(v0[j], 16), p1_ = __shfl_xor(v1[j], 16);
;                   if (fq < 2) { v0[j] = (fq == 0) ? (v0[j] * c0[j] - p0_ * s0[j]) : (v0[j] * c0[j] + p0_ * s0[j]);
;                                 v1[j] = (fq == 0) ? (v1[j] * c1[j] - p1_ * s1[j]) : (v1[j] * c1[j] + p1_ * s1[j]); } }
;               }
;             }
;             u32x4 w = {cvtpk(v0[0] * rs, v0[1] * rs), cvtpk(v0[2] * rs, v0[3] * rs), cvtpk(v1[0] * rs, v1[1] * rs), cvtpk(v1[2] * rs, v1[3] * rs)};
;             *reinterpret_cast<u32x4*>(Out + (size_t)row * ldo + bcol + bj * HALF + wc * 32 + fq * 8) = w; } }
.LBB0_201:
	v_pk_mul_f32 v[76:77], v[200:201], v[76:77] op_sel_hi:[0,1]
	v_pk_mul_f32 v[78:79], v[200:201], v[78:79] op_sel_hi:[0,1]
	v_pk_mul_f32 v[72:73], v[200:201], v[72:73] op_sel_hi:[0,1]
	v_cvt_pk_bf16_f32 v76, v76, v77
	v_cvt_pk_bf16_f32 v77, v78, v79
	v_cvt_pk_bf16_f32 v78, v72, v73
	v_pk_mul_f32 v[72:73], v[200:201], v[74:75] op_sel_hi:[0,1]
	v_mad_i64_i32 v[96:97], s[26:27], v106, s85, v[144:145]
	v_cvt_pk_bf16_f32 v79, v72, v73
	s_and_b64 vcc, exec, s[8:9]
	global_store_dwordx4 v[96:97], v[76:79], off
	s_cbranch_vccnz .LBB0_211
	global_load_dwordx4 v[76:79], v[108:109], off offset:48
	global_load_dwordx4 v[88:91], v[108:109], off offset:32
	global_load_dwordx4 v[72:75], v[108:109], off offset:16
	global_load_dwordx4 v[80:83], v[108:109], off
	v_and_b32_e32 v85, 64, v211
	v_xor_b32_e32 v84, 16, v211
	v_add_u32_e32 v85, 64, v85
	v_cmp_lt_i32_e32 vcc, v84, v85
	v_mov_b64_e32 v[94:95], v[66:67]
	v_mov_b64_e32 v[92:93], v[64:65]
	v_cndmask_b32_e32 v84, v211, v84, vcc
	v_lshlrev_b32_e32 v98, 2, v84
	ds_bpermute_b32 v100, v98, v68
	ds_bpermute_b32 v99, v98, v64
	v_mov_b64_e32 v[86:87], v[70:71]
	v_mov_b64_e32 v[84:85], v[68:69]
	s_and_saveexec_b64 s[26:27], s[4:5]
	s_cbranch_execz .LBB0_204
	s_waitcnt vmcnt(2) lgkmcnt(1)
	v_mul_f32_e32 v84, v88, v100
	v_cndmask_b32_e64 v88, v84, -v84, s[6:7]
	v_mov_b64_e32 v[86:87], v[70:71]
	s_waitcnt vmcnt(0)
	v_fmac_f32_e32 v88, v68, v80
	v_mov_b64_e32 v[84:85], v[68:69]
	s_waitcnt lgkmcnt(0)
	v_mul_f32_e32 v68, v76, v99
	v_cndmask_b32_e64 v68, v68, -v68, s[6:7]
	v_mov_b64_e32 v[94:95], v[66:67]
	v_fmac_f32_e32 v68, v64, v72
	v_mov_b64_e32 v[92:93], v[64:65]
	v_mov_b32_e32 v84, v88
	v_mov_b32_e32 v92, v68

; DEV unsigned cvtpk(float lo, float hi) { f32x2_t v = {lo, hi}; bf16x2_t b = __builtin_convertvector(v, bf16x2_t); return __builtin_bit_cast(unsigned, b); }
; template <int MODE>
; DEV void gemm_phase(const bf16_t* __restrict__ A, const bf16_t* __restrict__ Bt, int M, int N, int K, bf16_t* __restrict__ Out, int ldo,
;                     const float* __restrict__ rstd, const float* __restrict__ rope) {
;     ...
;           const int row = brow + ai * HALF + wr * 64 + m * 16 + fr;
;           float rs = 1.f; if constexpr (MODE == G_INPROJ) rs = rstd[row];
; #pragma unroll
;           for (int bj = 0; bj < 2; ++bj) {
;             f32x4 v0 = acc[ai][bj][m][0], v1 = acc[ai][bj][m][1];
;             if constexpr (MODE == G_INPROJ) {
;               if (ropet) {
;                 const f32x4 c0 = *reinterpret_cast<const f32x4*>(rope + (size_t)row * 16), c1 = *reinterpret_cast<const f32x4*>(rope + (size_t)row * 16 + 4);
;                 const f32x4 s0 = *reinterpret_cast<const f32x4*>(rope + (size_t)row * 16 + 8), s1 = *reinterpret_cast<const f32x4*>(rope + (size_t)row * 16 + 12);
; #pragma unroll
;                 for (int j = 0; j < 4; ++j) { const float p0_ = __shfl_xor(v0[j], 16), p1_ = __shfl_xor(v1[j], 16);
;                   if (fq < 2) { v0[j] = (fq == 0) ? (v0[j] * c0[j] - p0_ * s0[j]) : (v0[j] * c0[j] + p0_ * s0[j]);
;                                 v1[j] = (fq == 0) ? (v1[j] * c1[j] - p1_ * s1[j]) : (v1[j] * c1[j] + p1_ * s1[j]); } }
;               }
;             }
;             u32x4 w = {cvtpk(v0[0] * rs, v0[1] * rs), cvtpk(v0[2] * rs, v0[3] * rs), cvtpk(v1[0] * rs, v1[1] * rs), cvtpk(v1[2] * rs, v1[3] * rs)};
;             *reinterpret_cast<u32x4*>(Out + (size_t)row * ldo + bcol + bj * HALF + wc * 32 + fq * 8) = w; } }
.LBB0_211:
	v_mov_b32_e32 v201, v200
	v_pk_mul_f32 v[68:69], v[200:201], v[68:69]
	v_pk_mul_f32 v[70:71], v[200:201], v[70:71]
	v_pk_mul_f32 v[64:65], v[200:201], v[64:65]
	v_add_u32_e32 v90, 0x80, v164
	v_cvt_pk_bf16_f32 v68, v68, v69
	v_cvt_pk_bf16_f32 v69, v70, v71
	v_cvt_pk_bf16_f32 v70, v64, v65
	v_pk_mul_f32 v[64:65], v[200:201], v[66:67]
	v_ashrrev_i32_e32 v91, 31, v90
	v_cvt_pk_bf16_f32 v71, v64, v65
	v_lshl_add_u64 v[64:65], v[90:91], 2, s[68:69]
	v_lshlrev_b64 v[64:65], 6, v[90:91]
	v_lshl_add_u64 v[92:93], s[72:73], 0, v[64:65]
	s_and_b64 vcc, exec, s[8:9]
	global_store_dwordx4 v[96:97], v[68:71], off offset:256
	s_cbranch_vccnz .LBB0_221
	global_load_dwordx4 v[68:71], v[92:93], off offset:48
	global_load_dwordx4 v[80:83], v[92:93], off offset:32
	global_load_dwordx4 v[64:67], v[92:93], off offset:16
	global_load_dwordx4 v[72:75], v[92:93], off
	v_and_b32_e32 v77, 64, v211
	v_xor_b32_e32 v76, 16, v211
	v_add_u32_e32 v77, 64, v77
	v_cmp_lt_i32_e32 vcc, v76, v77
	v_mov_b64_e32 v[86:87], v[58:59]
	v_mov_b64_e32 v[84:85], v[56:57]
	v_cndmask_b32_e32 v76, v211, v76, vcc
	v_lshlrev_b32_e32 v89, 2, v76
	ds_bpermute_b32 v94, v89, v60
	ds_bpermute_b32 v91, v89, v56
	v_mov_b64_e32 v[78:79], v[62:63]
	v_mov_b64_e32 v[76:77], v[60:61]
	s_and_saveexec_b64 s[26:27], s[4:5]
	s_cbranch_execz .LBB0_214
	s_waitcnt vmcnt(2) lgkmcnt(1)
	v_mul_f32_e32 v76, v80, v94
	v_cndmask_b32_e64 v80, v76, -v76, s[6:7]
	v_mov_b64_e32 v[78:79], v[62:63]
	s_waitcnt vmcnt(0)
	v_fmac_f32_e32 v80, v60, v72
	v_mov_b64_e32 v[76:77], v[60:61]
	s_waitcnt lgkmcnt(0)
	v_mul_f32_e32 v60, v68, v91
	v_cndmask_b32_e64 v60, v60, -v60, s[6:7]
	v_mov_b64_e32 v[86:87], v[58:59]
	v_fmac_f32_e32 v60, v56, v64
	v_mov_b64_e32 v[84:85], v[56:57]
	v_mov_b32_e32 v76, v80
	v_mov_b32_e32 v84, v60

; DEV unsigned cvtpk(float lo, float hi) { f32x2_t v = {lo, hi}; bf16x2_t b = __builtin_convertvector(v, bf16x2_t); return __builtin_bit_cast(unsigned, b); }
; template <int MODE>
; DEV void gemm_phase(const bf16_t* __restrict__ A, const bf16_t* __restrict__ Bt, int M, int N, int K, bf16_t* __restrict__ Out, int ldo,
;                     const float* __restrict__ rstd, const float* __restrict__ rope) {
;     ...
;           const int row = brow + ai * HALF + wr * 64 + m * 16 + fr;
;           float rs = 1.f; if constexpr (MODE == G_INPROJ) rs = rstd[row];
; #pragma unroll
;           for (int bj = 0; bj < 2; ++bj) {
;             f32x4 v0 = acc[ai][bj][m][0], v1 = acc[ai][bj][m][1];
;             if constexpr (MODE == G_INPROJ) {
;               if (ropet) {
;                 const f32x4 c0 = *reinterpret_cast<const f32x4*>(rope + (size_t)row * 16), c1 = *reinterpret_cast<const f32x4*>(rope + (size_t)row * 16 + 4);
;                 const f32x4 s0 = *reinterpret_cast<const f32x4*>(rope + (size_t)row * 16 + 8), s1 = *reinterpret_cast<const f32x4*>(rope + (size_t)row * 16 + 12);
; #pragma unroll
;                 for (int j = 0; j < 4; ++j) { const float p0_ = __shfl_xor(v0[j], 16), p1_ = __shfl_xor(v1[j], 16);
;                   if (fq < 2) { v0[j] = (fq == 0) ? (v0[j] * c0[j] - p0_ * s0[j]) : (v0[j] * c0[j] + p0_ * s0[j]);
;                                 v1[j] = (fq == 0) ? (v1[j] * c1[j] - p1_ * s1[j]) : (v1[j] * c1[j] + p1_ * s1[j]); } }
;               }
;             }
;             u32x4 w = {cvtpk(v0[0] * rs, v0[1] * rs), cvtpk(v0[2] * rs, v0[3] * rs), cvtpk(v1[0] * rs, v1[1] * rs), cvtpk(v1[2] * rs, v1[3] * rs)};
;             *reinterpret_cast<u32x4*>(Out + (size_t)row * ldo + bcol + bj * HALF + wc * 32 + fq * 8) = w; } }
.LBB0_221:
	v_pk_mul_f32 v[60:61], v[202:203], v[60:61] op_sel_hi:[0,1]
	v_pk_mul_f32 v[62:63], v[202:203], v[62:63] op_sel_hi:[0,1]
	v_pk_mul_f32 v[56:57], v[202:203], v[56:57] op_sel_hi:[0,1]
	v_cvt_pk_bf16_f32 v60, v60, v61
	v_cvt_pk_bf16_f32 v61, v62, v63
	v_cvt_pk_bf16_f32 v62, v56, v57
	v_pk_mul_f32 v[56:57], v[202:203], v[58:59] op_sel_hi:[0,1]
	v_mad_i64_i32 v[80:81], s[26:27], v90, s85, v[144:145]
	v_cvt_pk_bf16_f32 v63, v56, v57
	s_and_b64 vcc, exec, s[8:9]
	global_store_dwordx4 v[80:81], v[60:63], off
	s_cbranch_vccnz .LBB0_231
	global_load_dwordx4 v[60:63], v[92:93], off offset:48
	global_load_dwordx4 v[72:75], v[92:93], off offset:32
	global_load_dwordx4 v[56:59], v[92:93], off offset:16
	global_load_dwordx4 v[64:67], v[92:93], off
	v_and_b32_e32 v69, 64, v211
	v_xor_b32_e32 v68, 16, v211
	v_add_u32_e32 v69, 64, v69
	v_cmp_lt_i32_e32 vcc, v68, v69
	v_mov_b64_e32 v[78:79], v[50:51]
	v_mov_b64_e32 v[76:77], v[48:49]
	v_cndmask_b32_e32 v68, v211, v68, vcc
	v_lshlrev_b32_e32 v82, 2, v68
	ds_bpermute_b32 v84, v82, v52
	ds_bpermute_b32 v83, v82, v48
	v_mov_b64_e32 v[70:71], v[54:55]
	v_mov_b64_e32 v[68:69], v[52:53]
	s_and_saveexec_b64 s[26:27], s[4:5]
	s_cbranch_execz .LBB0_224
	s_waitcnt vmcnt(2) lgkmcnt(1)
	v_mul_f32_e32 v68, v72, v84
	v_cndmask_b32_e64 v72, v68, -v68, s[6:7]
	v_mov_b64_e32 v[70:71], v[54:55]
	s_waitcnt vmcnt(0)
	v_fmac_f32_e32 v72, v52, v64
	v_mov_b64_e32 v[68:69], v[52:53]
	s_waitcnt lgkmcnt(0)
	v_mul_f32_e32 v52, v60, v83
	v_cndmask_b32_e64 v52, v52, -v52, s[6:7]
	v_mov_b64_e32 v[78:79], v[50:51]
	v_fmac_f32_e32 v52, v48, v56
	v_mov_b64_e32 v[76:77], v[48:49]
	v_mov_b32_e32 v68, v72
	v_mov_b32_e32 v76, v52

; DEV unsigned cvtpk(float lo, float hi) { f32x2_t v = {lo, hi}; bf16x2_t b = __builtin_convertvector(v, bf16x2_t); return __builtin_bit_cast(unsigned, b); }
; template <int MODE>
; DEV void gemm_phase(const bf16_t* __restrict__ A, const bf16_t* __restrict__ Bt, int M, int N, int K, bf16_t* __restrict__ Out, int ldo,
;                     const float* __restrict__ rstd, const float* __restrict__ rope) {
;     ...
;           const int row = brow + ai * HALF + wr * 64 + m * 16 + fr;
;           float rs = 1.f; if constexpr (MODE == G_INPROJ) rs = rstd[row];
; #pragma unroll
;           for (int bj = 0; bj < 2; ++bj) {
;             f32x4 v0 = acc[ai][bj][m][0], v1 = acc[ai][bj][m][1];
;             if constexpr (MODE == G_INPROJ) {
;               if (ropet) {
;                 const f32x4 c0 = *reinterpret_cast<const f32x4*>(rope + (size_t)row * 16), c1 = *reinterpret_cast<const f32x4*>(rope + (size_t)row * 16 + 4);
;                 const f32x4 s0 = *reinterpret_cast<const f32x4*>(rope + (size_t)row * 16 + 8), s1 = *reinterpret_cast<const f32x4*>(rope + (size_t)row * 16 + 12);
; #pragma unroll
;                 for (int j = 0; j < 4; ++j) { const float p0_ = __shfl_xor(v0[j], 16), p1_ = __shfl_xor(v1[j], 16);
;                   if (fq < 2) { v0[j] = (fq == 0) ? (v0[j] * c0[j] - p0_ * s0[j]) : (v0[j] * c0[j] + p0_ * s0[j]);
;                                 v1[j] = (fq == 0) ? (v1[j] * c1[j] - p1_ * s1[j]) : (v1[j] * c1[j] + p1_ * s1[j]); } }
;               }
;             }
;             u32x4 w = {cvtpk(v0[0] * rs, v0[1] * rs), cvtpk(v0[2] * rs, v0[3] * rs), cvtpk(v1[0] * rs, v1[1] * rs), cvtpk(v1[2] * rs, v1[3] * rs)};
;             *reinterpret_cast<u32x4*>(Out + (size_t)row * ldo + bcol + bj * HALF + wc * 32 + fq * 8) = w; } }
.LBB0_231:
	v_mov_b32_e32 v203, v202
	v_pk_mul_f32 v[52:53], v[202:203], v[52:53]
	v_pk_mul_f32 v[54:55], v[202:203], v[54:55]
	v_pk_mul_f32 v[48:49], v[202:203], v[48:49]
	v_add_u32_e32 v74, 0x90, v164
	v_cvt_pk_bf16_f32 v52, v52, v53
	v_cvt_pk_bf16_f32 v53, v54, v55
	v_cvt_pk_bf16_f32 v54, v48, v49
	v_pk_mul_f32 v[48:49], v[202:203], v[50:51]
	v_ashrrev_i32_e32 v75, 31, v74
	v_cvt_pk_bf16_f32 v55, v48, v49
	v_lshl_add_u64 v[48:49], v[74:75], 2, s[68:69]
	v_lshlrev_b64 v[48:49], 6, v[74:75]
	v_lshl_add_u64 v[76:77], s[72:73], 0, v[48:49]
	s_and_b64 vcc, exec, s[8:9]
	global_store_dwordx4 v[80:81], v[52:55], off offset:256
	s_cbranch_vccnz .LBB0_241
	global_load_dwordx4 v[52:55], v[76:77], off offset:48
	global_load_dwordx4 v[64:67], v[76:77], off offset:32
	global_load_dwordx4 v[48:51], v[76:77], off offset:16
	global_load_dwordx4 v[56:59], v[76:77], off
	v_and_b32_e32 v61, 64, v211
	v_xor_b32_e32 v60, 16, v211
	v_add_u32_e32 v61, 64, v61
	v_cmp_lt_i32_e32 vcc, v60, v61
	v_mov_b64_e32 v[70:71], v[42:43]
	v_mov_b64_e32 v[68:69], v[40:41]
	v_cndmask_b32_e32 v60, v211, v60, vcc
	v_lshlrev_b32_e32 v73, 2, v60
	ds_bpermute_b32 v78, v73, v44
	ds_bpermute_b32 v75, v73, v40
	v_mov_b64_e32 v[62:63], v[46:47]
	v_mov_b64_e32 v[60:61], v[44:45]
	s_and_saveexec_b64 s[26:27], s[4:5]
	s_cbranch_execz .LBB0_234
	s_waitcnt vmcnt(2) lgkmcnt(1)
	v_mul_f32_e32 v60, v64, v78
	v_cndmask_b32_e64 v64, v60, -v60, s[6:7]
	v_mov_b64_e32 v[62:63], v[46:47]
	s_waitcnt vmcnt(0)
	v_fmac_f32_e32 v64, v44, v56
	v_mov_b64_e32 v[60:61], v[44:45]
	s_waitcnt lgkmcnt(0)
	v_mul_f32_e32 v44, v52, v75
	v_cndmask_b32_e64 v44, v44, -v44, s[6:7]
	v_mov_b64_e32 v[70:71], v[42:43]
	v_fmac_f32_e32 v44, v40, v48
	v_mov_b64_e32 v[68:69], v[40:41]
	v_mov_b32_e32 v60, v64
	v_mov_b32_e32 v68, v44

; DEV unsigned cvtpk(float lo, float hi) { f32x2_t v = {lo, hi}; bf16x2_t b = __builtin_convertvector(v, bf16x2_t); return __builtin_bit_cast(unsigned, b); }
; template <int MODE>
; DEV void gemm_phase(const bf16_t* __restrict__ A, const bf16_t* __restrict__ Bt, int M, int N, int K, bf16_t* __restrict__ Out, int ldo,
;                     const float* __restrict__ rstd, const float* __restrict__ rope) {
;     ...
;           const int row = brow + ai * HALF + wr * 64 + m * 16 + fr;
;           float rs = 1.f; if constexpr (MODE == G_INPROJ) rs = rstd[row];
; #pragma unroll
;           for (int bj = 0; bj < 2; ++bj) {
;             f32x4 v0 = acc[ai][bj][m][0], v1 = acc[ai][bj][m][1];
;             if constexpr (MODE == G_INPROJ) {
;               if (ropet) {
;                 const f32x4 c0 = *reinterpret_cast<const f32x4*>(rope + (size_t)row * 16), c1 = *reinterpret_cast<const f32x4*>(rope + (size_t)row * 16 + 4);
;                 const f32x4 s0 = *reinterpret_cast<const f32x4*>(rope + (size_t)row * 16 + 8), s1 = *reinterpret_cast<const f32x4*>(rope + (size_t)row * 16 + 12);
; #pragma unroll
;                 for (int j = 0; j < 4; ++j) { const float p0_ = __shfl_xor(v0[j], 16), p1_ = __shfl_xor(v1[j], 16);
;                   if (fq < 2) { v0[j] = (fq == 0) ? (v0[j] * c0[j] - p0_ * s0[j]) : (v0[j] * c0[j] + p0_ * s0[j]);
;                                 v1[j] = (fq == 0) ? (v1[j] * c1[j] - p1_ * s1[j]) : (v1[j] * c1[j] + p1_ * s1[j]); } }
;               }
;             }
;             u32x4 w = {cvtpk(v0[0] * rs, v0[1] * rs), cvtpk(v0[2] * rs, v0[3] * rs), cvtpk(v1[0] * rs, v1[1] * rs), cvtpk(v1[2] * rs, v1[3] * rs)};
;             *reinterpret_cast<u32x4*>(Out + (size_t)row * ldo + bcol + bj * HALF + wc * 32 + fq * 8) = w; } }
.LBB0_241:
	v_pk_mul_f32 v[44:45], v[204:205], v[44:45] op_sel_hi:[0,1]
	v_pk_mul_f32 v[46:47], v[204:205], v[46:47] op_sel_hi:[0,1]
	v_pk_mul_f32 v[40:41], v[204:205], v[40:41] op_sel_hi:[0,1]
	v_cvt_pk_bf16_f32 v44, v44, v45
	v_cvt_pk_bf16_f32 v45, v46, v47
	v_cvt_pk_bf16_f32 v46, v40, v41
	v_pk_mul_f32 v[40:41], v[204:205], v[42:43] op_sel_hi:[0,1]
	v_mad_i64_i32 v[64:65], s[26:27], v74, s85, v[144:145]
	v_cvt_pk_bf16_f32 v47, v40, v41
	s_and_b64 vcc, exec, s[8:9]
	global_store_dwordx4 v[64:65], v[44:47], off
	s_cbranch_vccnz .LBB0_251
	global_load_dwordx4 v[44:47], v[76:77], off offset:48
	global_load_dwordx4 v[56:59], v[76:77], off offset:32
	global_load_dwordx4 v[40:43], v[76:77], off offset:16
	global_load_dwordx4 v[48:51], v[76:77], off
	v_and_b32_e32 v53, 64, v211
	v_xor_b32_e32 v52, 16, v211
	v_add_u32_e32 v53, 64, v53
	v_cmp_lt_i32_e32 vcc, v52, v53
	v_mov_b64_e32 v[62:63], v[34:35]
	v_mov_b64_e32 v[60:61], v[32:33]
	v_cndmask_b32_e32 v52, v211, v52, vcc
	v_lshlrev_b32_e32 v66, 2, v52
	ds_bpermute_b32 v68, v66, v36
	ds_bpermute_b32 v67, v66, v32
	v_mov_b64_e32 v[54:55], v[38:39]
	v_mov_b64_e32 v[52:53], v[36:37]
	s_and_saveexec_b64 s[26:27], s[4:5]
	s_cbranch_execz .LBB0_244
	s_waitcnt vmcnt(2) lgkmcnt(1)
	v_mul_f32_e32 v52, v56, v68
	v_cndmask_b32_e64 v56, v52, -v52, s[6:7]
	v_mov_b64_e32 v[54:55], v[38:39]
	s_waitcnt vmcnt(0)
	v_fmac_f32_e32 v56, v36, v48
	v_mov_b64_e32 v[52:53], v[36:37]
	s_waitcnt lgkmcnt(0)
	v_mul_f32_e32 v36, v44, v67
	v_cndmask_b32_e64 v36, v36, -v36, s[6:7]
	v_mov_b64_e32 v[62:63], v[34:35]
	v_fmac_f32_e32 v36, v32, v40
	v_mov_b64_e32 v[60:61], v[32:33]
	v_mov_b32_e32 v52, v56
	v_mov_b32_e32 v60, v36

; DEV unsigned cvtpk(float lo, float hi) { f32x2_t v = {lo, hi}; bf16x2_t b = __builtin_convertvector(v, bf16x2_t); return __builtin_bit_cast(unsigned, b); }
; template <int MODE>
; DEV void gemm_phase(const bf16_t* __restrict__ A, const bf16_t* __restrict__ Bt, int M, int N, int K, bf16_t* __restrict__ Out, int ldo,
;                     const float* __restrict__ rstd, const float* __restrict__ rope) {
;     ...
;           const int row = brow + ai * HALF + wr * 64 + m * 16 + fr;
;           float rs = 1.f; if constexpr (MODE == G_INPROJ) rs = rstd[row];
; #pragma unroll
;           for (int bj = 0; bj < 2; ++bj) {
;             f32x4 v0 = acc[ai][bj][m][0], v1 = acc[ai][bj][m][1];
;             if constexpr (MODE == G_INPROJ) {
;               if (ropet) {
;                 const f32x4 c0 = *reinterpret_cast<const f32x4*>(rope + (size_t)row * 16), c1 = *reinterpret_cast<const f32x4*>(rope + (size_t)row * 16 + 4);
;                 const f32x4 s0 = *reinterpret_cast<const f32x4*>(rope + (size_t)row * 16 + 8), s1 = *reinterpret_cast<const f32x4*>(rope + (size_t)row * 16 + 12);
; #pragma unroll
;                 for (int j = 0; j < 4; ++j) { const float p0_ = __shfl_xor(v0[j], 16), p1_ = __shfl_xor(v1[j], 16);
;                   if (fq < 2) { v0[j] = (fq == 0) ? (v0[j] * c0[j] - p0_ * s0[j]) : (v0[j] * c0[j] + p0_ * s0[j]);
;                                 v1[j] = (fq == 0) ? (v1[j] * c1[j] - p1_ * s1[j]) : (v1[j] * c1[j] + p1_ * s1[j]); } }
;               }
;             }
;             u32x4 w = {cvtpk(v0[0] * rs, v0[1] * rs), cvtpk(v0[2] * rs, v0[3] * rs), cvtpk(v1[0] * rs, v1[1] * rs), cvtpk(v1[2] * rs, v1[3] * rs)};
;             *reinterpret_cast<u32x4*>(Out + (size_t)row * ldo + bcol + bj * HALF + wc * 32 + fq * 8) = w; } }
.LBB0_251:
	v_mov_b32_e32 v205, v204
	v_pk_mul_f32 v[36:37], v[204:205], v[36:37]
	v_pk_mul_f32 v[38:39], v[204:205], v[38:39]
	v_pk_mul_f32 v[32:33], v[204:205], v[32:33]
	v_add_u32_e32 v58, 0xa0, v164
	v_cvt_pk_bf16_f32 v36, v36, v37
	v_cvt_pk_bf16_f32 v37, v38, v39
	v_cvt_pk_bf16_f32 v38, v32, v33
	v_pk_mul_f32 v[32:33], v[204:205], v[34:35]
	v_ashrrev_i32_e32 v59, 31, v58
	v_cvt_pk_bf16_f32 v39, v32, v33
	v_lshl_add_u64 v[32:33], v[58:59], 2, s[68:69]
	v_lshlrev_b64 v[32:33], 6, v[58:59]
	v_lshl_add_u64 v[60:61], s[72:73], 0, v[32:33]
	s_and_b64 vcc, exec, s[8:9]
	global_store_dwordx4 v[64:65], v[36:39], off offset:256
	s_cbranch_vccnz .LBB0_261
	global_load_dwordx4 v[36:39], v[60:61], off offset:48
	global_load_dwordx4 v[48:51], v[60:61], off offset:32
	global_load_dwordx4 v[32:35], v[60:61], off offset:16
	global_load_dwordx4 v[40:43], v[60:61], off
	v_and_b32_e32 v45, 64, v211
	v_xor_b32_e32 v44, 16, v211
	v_add_u32_e32 v45, 64, v45
	v_cmp_lt_i32_e32 vcc, v44, v45
	v_mov_b64_e32 v[54:55], v[26:27]
	v_mov_b64_e32 v[52:53], v[24:25]
	v_cndmask_b32_e32 v44, v211, v44, vcc
	v_lshlrev_b32_e32 v57, 2, v44
	ds_bpermute_b32 v62, v57, v28
	ds_bpermute_b32 v59, v57, v24
	v_mov_b64_e32 v[46:47], v[30:31]
	v_mov_b64_e32 v[44:45], v[28:29]
	s_and_saveexec_b64 s[26:27], s[4:5]
	s_cbranch_execz .LBB0_254
	s_waitcnt vmcnt(2) lgkmcnt(1)
	v_mul_f32_e32 v44, v48, v62
	v_cndmask_b32_e64 v48, v44, -v44, s[6:7]
	v_mov_b64_e32 v[46:47], v[30:31]
	s_waitcnt vmcnt(0)
	v_fmac_f32_e32 v48, v28, v40
	v_mov_b64_e32 v[44:45], v[28:29]
	s_waitcnt lgkmcnt(0)
	v_mul_f32_e32 v28, v36, v59
	v_cndmask_b32_e64 v28, v28, -v28, s[6:7]
	v_mov_b64_e32 v[54:55], v[26:27]
	v_fmac_f32_e32 v28, v24, v32
	v_mov_b64_e32 v[52:53], v[24:25]
	v_mov_b32_e32 v44, v48
	v_mov_b32_e32 v52, v28

; DEV unsigned cvtpk(float lo, float hi) { f32x2_t v = {lo, hi}; bf16x2_t b = __builtin_convertvector(v, bf16x2_t); return __builtin_bit_cast(unsigned, b); }
; template <int MODE>
; DEV void gemm_phase(const bf16_t* __restrict__ A, const bf16_t* __restrict__ Bt, int M, int N, int K, bf16_t* __restrict__ Out, int ldo,
;                     const float* __restrict__ rstd, const float* __restrict__ rope) {
;     ...
;           const int row = brow + ai * HALF + wr * 64 + m * 16 + fr;
;           float rs = 1.f; if constexpr (MODE == G_INPROJ) rs = rstd[row];
; #pragma unroll
;           for (int bj = 0; bj < 2; ++bj) {
;             f32x4 v0 = acc[ai][bj][m][0], v1 = acc[ai][bj][m][1];
;             if constexpr (MODE == G_INPROJ) {
;               if (ropet) {
;                 const f32x4 c0 = *reinterpret_cast<const f32x4*>(rope + (size_t)row * 16), c1 = *reinterpret_cast<const f32x4*>(rope + (size_t)row * 16 + 4);
;                 const f32x4 s0 = *reinterpret_cast<const f32x4*>(rope + (size_t)row * 16 + 8), s1 = *reinterpret_cast<const f32x4*>(rope + (size_t)row * 16 + 12);
; #pragma unroll
;                 for (int j = 0; j < 4; ++j) { const float p0_ = __shfl_xor(v0[j], 16), p1_ = __shfl_xor(v1[j], 16);
;                   if (fq < 2) { v0[j] = (fq == 0) ? (v0[j] * c0[j] - p0_ * s0[j]) : (v0[j] * c0[j] + p0_ * s0[j]);
;                                 v1[j] = (fq == 0) ? (v1[j] * c1[j] - p1_ * s1[j]) : (v1[j] * c1[j] + p1_ * s1[j]); } }
;               }
;             }
;             u32x4 w = {cvtpk(v0[0] * rs, v0[1] * rs), cvtpk(v0[2] * rs, v0[3] * rs), cvtpk(v1[0] * rs, v1[1] * rs), cvtpk(v1[2] * rs, v1[3] * rs)};
;             *reinterpret_cast<u32x4*>(Out + (size_t)row * ldo + bcol + bj * HALF + wc * 32 + fq * 8) = w; } }
.LBB0_261:
	v_pk_mul_f32 v[28:29], v[206:207], v[28:29] op_sel_hi:[0,1]
	v_pk_mul_f32 v[30:31], v[206:207], v[30:31] op_sel_hi:[0,1]
	v_pk_mul_f32 v[24:25], v[206:207], v[24:25] op_sel_hi:[0,1]
	v_cvt_pk_bf16_f32 v28, v28, v29
	v_cvt_pk_bf16_f32 v29, v30, v31
	v_cvt_pk_bf16_f32 v30, v24, v25
	v_pk_mul_f32 v[24:25], v[206:207], v[26:27] op_sel_hi:[0,1]
	v_mad_i64_i32 v[48:49], s[26:27], v58, s85, v[144:145]
	v_cvt_pk_bf16_f32 v31, v24, v25
	s_and_b64 vcc, exec, s[8:9]
	global_store_dwordx4 v[48:49], v[28:31], off
	s_cbranch_vccnz .LBB0_271
	global_load_dwordx4 v[28:31], v[60:61], off offset:48
	global_load_dwordx4 v[40:43], v[60:61], off offset:32
	global_load_dwordx4 v[24:27], v[60:61], off offset:16
	global_load_dwordx4 v[32:35], v[60:61], off
	v_and_b32_e32 v37, 64, v211
	v_xor_b32_e32 v36, 16, v211
	v_add_u32_e32 v37, 64, v37
	v_cmp_lt_i32_e32 vcc, v36, v37
	v_mov_b64_e32 v[46:47], v[18:19]
	v_mov_b64_e32 v[44:45], v[16:17]
	v_cndmask_b32_e32 v36, v211, v36, vcc
	v_lshlrev_b32_e32 v50, 2, v36
	ds_bpermute_b32 v52, v50, v20
	ds_bpermute_b32 v51, v50, v16
	v_mov_b64_e32 v[38:39], v[22:23]
	v_mov_b64_e32 v[36:37], v[20:21]
	s_and_saveexec_b64 s[26:27], s[4:5]
	s_cbranch_execz .LBB0_264
	s_waitcnt vmcnt(2) lgkmcnt(1)
	v_mul_f32_e32 v36, v40, v52
	v_cndmask_b32_e64 v40, v36, -v36, s[6:7]
	v_mov_b64_e32 v[38:39], v[22:23]
	s_waitcnt vmcnt(0)
	v_fmac_f32_e32 v40, v20, v32
	v_mov_b64_e32 v[36:37], v[20:21]
	s_waitcnt lgkmcnt(0)
	v_mul_f32_e32 v20, v28, v51
	v_cndmask_b32_e64 v20, v20, -v20, s[6:7]
	v_mov_b64_e32 v[46:47], v[18:19]
	v_fmac_f32_e32 v20, v16, v24
	v_mov_b64_e32 v[44:45], v[16:17]
	v_mov_b32_e32 v36, v40
	v_mov_b32_e32 v44, v20

; DEV unsigned cvtpk(float lo, float hi) { f32x2_t v = {lo, hi}; bf16x2_t b = __builtin_convertvector(v, bf16x2_t); return __builtin_bit_cast(unsigned, b); }
; template <int MODE>
; DEV void gemm_phase(const bf16_t* __restrict__ A, const bf16_t* __restrict__ Bt, int M, int N, int K, bf16_t* __restrict__ Out, int ldo,
;                     const float* __restrict__ rstd, const float* __restrict__ rope) {
;     ...
;           const int row = brow + ai * HALF + wr * 64 + m * 16 + fr;
;           float rs = 1.f; if constexpr (MODE == G_INPROJ) rs = rstd[row];
; #pragma unroll
;           for (int bj = 0; bj < 2; ++bj) {
;             f32x4 v0 = acc[ai][bj][m][0], v1 = acc[ai][bj][m][1];
;             if constexpr (MODE == G_INPROJ) {
;               if (ropet) {
;                 const f32x4 c0 = *reinterpret_cast<const f32x4*>(rope + (size_t)row * 16), c1 = *reinterpret_cast<const f32x4*>(rope + (size_t)row * 16 + 4);
;                 const f32x4 s0 = *reinterpret_cast<const f32x4*>(rope + (size_t)row * 16 + 8), s1 = *reinterpret_cast<const f32x4*>(rope + (size_t)row * 16 + 12);
; #pragma unroll
;                 for (int j = 0; j < 4; ++j) { const float p0_ = __shfl_xor(v0[j], 16), p1_ = __shfl_xor(v1[j], 16);
;                   if (fq < 2) { v0[j] = (fq == 0) ? (v0[j] * c0[j] - p0_ * s0[j]) : (v0[j] * c0[j] + p0_ * s0[j]);
;                                 v1[j] = (fq == 0) ? (v1[j] * c1[j] - p1_ * s1[j]) : (v1[j] * c1[j] + p1_ * s1[j]); } }
;               }
;             }
;             u32x4 w = {cvtpk(v0[0] * rs, v0[1] * rs), cvtpk(v0[2] * rs, v0[3] * rs), cvtpk(v1[0] * rs, v1[1] * rs), cvtpk(v1[2] * rs, v1[3] * rs)};
;             *reinterpret_cast<u32x4*>(Out + (size_t)row * ldo + bcol + bj * HALF + wc * 32 + fq * 8) = w; } }
.LBB0_271:
	v_mov_b32_e32 v207, v206
	v_pk_mul_f32 v[20:21], v[206:207], v[20:21]
	v_pk_mul_f32 v[22:23], v[206:207], v[22:23]
	v_pk_mul_f32 v[16:17], v[206:207], v[16:17]
	v_add_u32_e32 v42, 0xb0, v164
	v_cvt_pk_bf16_f32 v20, v20, v21
	v_cvt_pk_bf16_f32 v21, v22, v23
	v_cvt_pk_bf16_f32 v22, v16, v17
	v_pk_mul_f32 v[16:17], v[206:207], v[18:19]
	v_ashrrev_i32_e32 v43, 31, v42
	v_cvt_pk_bf16_f32 v23, v16, v17
	v_lshl_add_u64 v[16:17], v[42:43], 2, s[68:69]
	v_lshlrev_b64 v[16:17], 6, v[42:43]
	v_lshl_add_u64 v[44:45], s[72:73], 0, v[16:17]
	s_and_b64 vcc, exec, s[8:9]
	global_store_dwordx4 v[48:49], v[20:23], off offset:256
	s_cbranch_vccnz .LBB0_281
	global_load_dwordx4 v[20:23], v[44:45], off offset:48
	global_load_dwordx4 v[32:35], v[44:45], off offset:32
	global_load_dwordx4 v[16:19], v[44:45], off offset:16
	global_load_dwordx4 v[24:27], v[44:45], off
	v_and_b32_e32 v29, 64, v211
	v_xor_b32_e32 v28, 16, v211
	v_add_u32_e32 v29, 64, v29
	v_cmp_lt_i32_e32 vcc, v28, v29
	v_mov_b64_e32 v[38:39], v[10:11]
	v_mov_b64_e32 v[36:37], v[8:9]
	v_cndmask_b32_e32 v28, v211, v28, vcc
	v_lshlrev_b32_e32 v41, 2, v28
	ds_bpermute_b32 v46, v41, v12
	ds_bpermute_b32 v43, v41, v8
	v_mov_b64_e32 v[30:31], v[14:15]
	v_mov_b64_e32 v[28:29], v[12:13]
	s_and_saveexec_b64 s[26:27], s[4:5]
	s_cbranch_execz .LBB0_274
	s_waitcnt vmcnt(2) lgkmcnt(1)
	v_mul_f32_e32 v28, v32, v46
	v_cndmask_b32_e64 v32, v28, -v28, s[6:7]
	v_mov_b64_e32 v[30:31], v[14:15]
	s_waitcnt vmcnt(0)
	v_fmac_f32_e32 v32, v12, v24
	v_mov_b64_e32 v[28:29], v[12:13]
	s_waitcnt lgkmcnt(0)
	v_mul_f32_e32 v12, v20, v43
	v_cndmask_b32_e64 v12, v12, -v12, s[6:7]
	v_mov_b64_e32 v[38:39], v[10:11]
	v_fmac_f32_e32 v12, v8, v16
	v_mov_b64_e32 v[36:37], v[8:9]
	v_mov_b32_e32 v28, v32
	v_mov_b32_e32 v36, v12

; DEV unsigned cvtpk(float lo, float hi) { f32x2_t v = {lo, hi}; bf16x2_t b = __builtin_convertvector(v, bf16x2_t); return __builtin_bit_cast(unsigned, b); }
; template <int MODE>
; DEV void gemm_phase(const bf16_t* __restrict__ A, const bf16_t* __restrict__ Bt, int M, int N, int K, bf16_t* __restrict__ Out, int ldo,
;                     const float* __restrict__ rstd, const float* __restrict__ rope) {
;     ...
;           const int row = brow + ai * HALF + wr * 64 + m * 16 + fr;
;           float rs = 1.f; if constexpr (MODE == G_INPROJ) rs = rstd[row];
; #pragma unroll
;           for (int bj = 0; bj < 2; ++bj) {
;             f32x4 v0 = acc[ai][bj][m][0], v1 = acc[ai][bj][m][1];
;             if constexpr (MODE == G_INPROJ) {
;               if (ropet) {
;                 const f32x4 c0 = *reinterpret_cast<const f32x4*>(rope + (size_t)row * 16), c1 = *reinterpret_cast<const f32x4*>(rope + (size_t)row * 16 + 4);
;                 const f32x4 s0 = *reinterpret_cast<const f32x4*>(rope + (size_t)row * 16 + 8), s1 = *reinterpret_cast<const f32x4*>(rope + (size_t)row * 16 + 12);
; #pragma unroll
;                 for (int j = 0; j < 4; ++j) { const float p0_ = __shfl_xor(v0[j], 16), p1_ = __shfl_xor(v1[j], 16);
;                   if (fq < 2) { v0[j] = (fq == 0) ? (v0[j] * c0[j] - p0_ * s0[j]) : (v0[j] * c0[j] + p0_ * s0[j]);
;                                 v1[j] = (fq == 0) ? (v1[j] * c1[j] - p1_ * s1[j]) : (v1[j] * c1[j] + p1_ * s1[j]); } }
;               }
;             }
;             u32x4 w = {cvtpk(v0[0] * rs, v0[1] * rs), cvtpk(v0[2] * rs, v0[3] * rs), cvtpk(v1[0] * rs, v1[1] * rs), cvtpk(v1[2] * rs, v1[3] * rs)};
;             *reinterpret_cast<u32x4*>(Out + (size_t)row * ldo + bcol + bj * HALF + wc * 32 + fq * 8) = w; } }
.LBB0_281:
	v_pk_mul_f32 v[12:13], v[208:209], v[12:13] op_sel_hi:[0,1]
	v_pk_mul_f32 v[14:15], v[208:209], v[14:15] op_sel_hi:[0,1]
	v_pk_mul_f32 v[8:9], v[208:209], v[8:9] op_sel_hi:[0,1]
	v_cvt_pk_bf16_f32 v12, v12, v13
	v_cvt_pk_bf16_f32 v13, v14, v15
	v_cvt_pk_bf16_f32 v14, v8, v9
	v_pk_mul_f32 v[8:9], v[208:209], v[10:11] op_sel_hi:[0,1]
	v_mad_i64_i32 v[32:33], s[26:27], v42, s85, v[144:145]
	v_cvt_pk_bf16_f32 v15, v8, v9
	s_and_b64 vcc, exec, s[8:9]
	global_store_dwordx4 v[32:33], v[12:15], off
	s_cbranch_vccnz .LBB0_291
	global_load_dwordx4 v[12:15], v[44:45], off offset:48
	global_load_dwordx4 v[24:27], v[44:45], off offset:32
	global_load_dwordx4 v[8:11], v[44:45], off offset:16
	global_load_dwordx4 v[16:19], v[44:45], off
	v_and_b32_e32 v21, 64, v211
	v_xor_b32_e32 v20, 16, v211
	v_add_u32_e32 v21, 64, v21
	v_cmp_lt_i32_e32 vcc, v20, v21
	v_mov_b64_e32 v[30:31], v[2:3]
	v_mov_b64_e32 v[28:29], v[0:1]
	v_cndmask_b32_e32 v20, v211, v20, vcc
	v_lshlrev_b32_e32 v34, 2, v20
	ds_bpermute_b32 v36, v34, v4
	ds_bpermute_b32 v35, v34, v0
	v_mov_b64_e32 v[22:23], v[6:7]
	v_mov_b64_e32 v[20:21], v[4:5]
	s_and_saveexec_b64 s[8:9], s[4:5]
	s_cbranch_execz .LBB0_284
	s_waitcnt vmcnt(2) lgkmcnt(1)
	v_mul_f32_e32 v20, v24, v36
	v_cndmask_b32_e64 v24, v20, -v20, s[6:7]
	v_mov_b64_e32 v[22:23], v[6:7]
	s_waitcnt vmcnt(0)
	v_fmac_f32_e32 v24, v4, v16
	v_mov_b64_e32 v[20:21], v[4:5]
	s_waitcnt lgkmcnt(0)
	v_mul_f32_e32 v4, v12, v35
	v_cndmask_b32_e64 v4, v4, -v4, s[6:7]
	v_mov_b64_e32 v[30:31], v[2:3]
	v_fmac_f32_e32 v4, v0, v8
	v_mov_b64_e32 v[28:29], v[0:1]
	v_mov_b32_e32 v20, v24
	v_mov_b32_e32 v28, v4

; DEV unsigned cvtpk(float lo, float hi) { f32x2_t v = {lo, hi}; bf16x2_t b = __builtin_convertvector(v, bf16x2_t); return __builtin_bit_cast(unsigned, b); }
; #define BAR __builtin_amdgcn_s_barrier()
; template <int MODE>
; DEV void gemm_phase(const bf16_t* __restrict__ A, const bf16_t* __restrict__ Bt, int M, int N, int K, bf16_t* __restrict__ Out, int ldo,
;                     const float* __restrict__ rstd, const float* __restrict__ rope) {
;     ...
;           const int row = brow + ai * HALF + wr * 64 + m * 16 + fr;
;           float rs = 1.f; if constexpr (MODE == G_INPROJ) rs = rstd[row];
; #pragma unroll
;           for (int bj = 0; bj < 2; ++bj) {
;             f32x4 v0 = acc[ai][bj][m][0], v1 = acc[ai][bj][m][1];
;             if constexpr (MODE == G_INPROJ) {
;               if (ropet) {
;                 const f32x4 c0 = *reinterpret_cast<const f32x4*>(rope + (size_t)row * 16), c1 = *reinterpret_cast<const f32x4*>(rope + (size_t)row * 16 + 4);
;                 const f32x4 s0 = *reinterpret_cast<const f32x4*>(rope + (size_t)row * 16 + 8), s1 = *reinterpret_cast<const f32x4*>(rope + (size_t)row * 16 + 12);
; #pragma unroll
;                 for (int j = 0; j < 4; ++j) { const float p0_ = __shfl_xor(v0[j], 16), p1_ = __shfl_xor(v1[j], 16);
;                   if (fq < 2) { v0[j] = (fq == 0) ? (v0[j] * c0[j] - p0_ * s0[j]) : (v0[j] * c0[j] + p0_ * s0[j]);
;                                 v1[j] = (fq == 0) ? (v1[j] * c1[j] - p1_ * s1[j]) : (v1[j] * c1[j] + p1_ * s1[j]); } }
;               }
;             }
;             u32x4 w = {cvtpk(v0[0] * rs, v0[1] * rs), cvtpk(v0[2] * rs, v0[3] * rs), cvtpk(v1[0] * rs, v1[1] * rs), cvtpk(v1[2] * rs, v1[3] * rs)};
;             *reinterpret_cast<u32x4*>(Out + (size_t)row * ldo + bcol + bj * HALF + wc * 32 + fq * 8) = w; } }
;     ...
;     if (!has_next) break;
; #pragma unroll
;     for (int a = 0; a < 2; ++a)
; #pragma unroll
;       for (int b = 0; b < 2; ++b)
; #pragma unroll
;         for (int m = 0; m < 4; ++m)
; #pragma unroll
;           for (int n = 0; n < 2; ++n) acc[a][b][m][n] = (f32x4){0.f, 0.f, 0.f, 0.f};
;     pm = npm; pn = npn; cA = nA; cB = nB; L += (int)gridDim.x;
;     if (wr == 1) BAR;
.LBB0_291:
	v_mov_b32_e32 v209, v208
	v_pk_mul_f32 v[4:5], v[208:209], v[4:5]
	v_pk_mul_f32 v[6:7], v[208:209], v[6:7]
	v_pk_mul_f32 v[0:1], v[208:209], v[0:1]
	v_cvt_pk_bf16_f32 v4, v4, v5
	v_cvt_pk_bf16_f32 v5, v6, v7
	v_cvt_pk_bf16_f32 v6, v0, v1
	v_pk_mul_f32 v[0:1], v[208:209], v[2:3]
	s_mov_b64 s[8:9], -1
	v_cvt_pk_bf16_f32 v7, v0, v1
	s_and_b64 vcc, exec, s[16:17]
	global_store_dwordx4 v[32:33], v[4:7], off offset:256
	s_cbranch_vccz .LBB0_124
	s_and_b64 vcc, exec, s[10:11]
	s_cbranch_vccz .LBB0_123
	s_barrier
	s_branch .LBB0_123

.LBB0_369:
	s_and_b32 s22, s23, 3
	v_lshl_add_u32 v84, s22, 13, v229
	v_add_u32_e32 v86, v84, v230
	v_add_u32_e32 v87, v84, v231
	ds_read_b128 v[176:179], v228
	ds_read_b128 v[160:163], v86
	ds_read_b128 v[180:183], v228 offset:2048
	ds_read_b128 v[164:167], v87
	ds_read_b128 v[184:187], v228 offset:1024
	ds_read_b128 v[188:191], v228 offset:3072
	ds_read_b128 v[168:171], v86 offset:512
	ds_read_b128 v[172:175], v87 offset:512
	ds_read_b128 v[140:143], v86 offset:4096
	ds_read_b128 v[144:147], v87 offset:4096
	s_add_i32 s21, s23, 2
	s_min_i32 s12, s21, 0xff
	s_mul_i32 s0, s12, 0xc0000
	s_add_u32 s0, s86, s0
	s_addc_u32 s1, s87, 0
	s_and_b32 s12, s12, 3
	s_lshl_b32 s13, s12, 13
	s_lshl_b32 s12, s12, 14
	v_mov_b32_e32 v80, v232
	v_mov_b32_e32 v81, v234
	v_mov_b32_e32 v82, v233
	s_add_i32 m0, s17, s13
	s_add_i32 s12, s18, s12
	s_nop 0
	global_load_lds_dwordx4 v80, s[0:1]
	s_mov_b32 m0, s12
	s_nop 0
	global_load_lds_dwordx4 v82, s[0:1]
	s_add_i32 m0, s12, 0x2000
	s_nop 0
	global_load_lds_dwordx4 v81, s[0:1]
	s_and_b32 s0, s19, 0xc000
	v_add_u32_e32 v212, s0, v223
	v_add_u32_e32 v213, s0, v224
	v_cvt_pk_bf16_f32 v120, v241, v244
	v_cvt_pk_bf16_f32 v121, v245, v247
	v_cvt_pk_bf16_f32 v122, v240, v242
	v_cvt_pk_bf16_f32 v123, v243, v246
	v_cvt_pk_bf16_f32 v112, v153, v156
	v_cvt_pk_bf16_f32 v113, v158, v159
	v_cvt_pk_bf16_f32 v114, v152, v154
	v_cvt_pk_bf16_f32 v115, v155, v157
	v_cvt_pk_bf16_f32 v124, v137, v148
	v_cvt_pk_bf16_f32 v125, v149, v151
	v_cvt_pk_bf16_f32 v126, v132, v136
	v_cvt_pk_bf16_f32 v127, v139, v150
	v_cvt_pk_bf16_f32 v116, v129, v134
	v_cvt_pk_bf16_f32 v117, v135, v138
	v_cvt_pk_bf16_f32 v118, v128, v130
	v_cvt_pk_bf16_f32 v119, v131, v133
	s_andn2_b64 vcc, exec, s[6:7]
	s_cbranch_vccz .Lh1a_resc
.Lh1a_resc_ret:
	s_mov_b32 s82, s80
	s_mov_b32 s83, s80
	s_mov_b32 s81, s80
	v_mov_b64_e32 v[154:155], s[82:83]
	v_mov_b64_e32 v[152:153], s[80:81]
	ds_read_b128 v[240:243], v86 offset:4608
	ds_read_b128 v[244:247], v87 offset:4608
	v_mfma_f32_16x16x32_bf16 v[68:71], v[120:123], v[152:155], v[68:71]
	v_mfma_f32_16x16x32_bf16 v[56:59], v[124:127], v[152:155], v[56:59]
	v_mfma_f32_16x16x32_bf16 v[68:71], v[112:115], v[152:155], v[68:71]
	v_mfma_f32_16x16x32_bf16 v[56:59], v[116:119], v[152:155], v[56:59]
	s_waitcnt lgkmcnt(6)
	ds_read_b64_tr_b16 v[128:129], v212
	ds_read_b64_tr_b16 v[130:131], v212 offset:4096
	ds_read_b64_tr_b16 v[132:133], v212 offset:8192
	ds_read_b64_tr_b16 v[134:135], v212 offset:12288
	v_mfma_f32_16x16x32_bf16 v[84:87], v[160:163], v[176:179], v[72:75]
	v_mfma_f32_16x16x32_bf16 v[80:83], v[160:163], v[180:183], v[76:79]
	v_mfma_f32_16x16x32_bf16 v[84:87], v[164:167], v[184:187], v[84:87]
	v_mfma_f32_16x16x32_bf16 v[80:83], v[164:167], v[188:191], v[80:83]
	s_waitcnt lgkmcnt(8)
	ds_read_b64_tr_b16 v[136:137], v213
	ds_read_b64_tr_b16 v[138:139], v213 offset:4096
	ds_read_b64_tr_b16 v[148:149], v213 offset:8192
	ds_read_b64_tr_b16 v[150:151], v213 offset:12288
	v_mfma_f32_16x16x32_bf16 v[96:99], v[168:171], v[176:179], v[72:75]
	v_mfma_f32_16x16x32_bf16 v[88:91], v[168:171], v[180:183], v[76:79]
	v_mfma_f32_16x16x32_bf16 v[96:99], v[172:175], v[184:187], v[96:99]
	v_mfma_f32_16x16x32_bf16 v[88:91], v[172:175], v[188:191], v[88:91]
	s_waitcnt lgkmcnt(10)
	ds_read_b64_tr_b16 v[152:153], v212 offset:1024
	ds_read_b64_tr_b16 v[154:155], v212 offset:5120
	ds_read_b64_tr_b16 v[156:157], v212 offset:9216
	ds_read_b64_tr_b16 v[158:159], v212 offset:13312
	v_mfma_f32_16x16x32_bf16 v[100:103], v[140:143], v[176:179], v[72:75]
	v_mfma_f32_16x16x32_bf16 v[92:95], v[140:143], v[180:183], v[76:79]
	v_mfma_f32_16x16x32_bf16 v[100:103], v[144:147], v[184:187], v[100:103]
	v_mfma_f32_16x16x32_bf16 v[92:95], v[144:147], v[188:191], v[92:95]
	s_waitcnt lgkmcnt(12)
	v_mfma_f32_16x16x32_bf16 v[108:111], v[240:243], v[176:179], v[72:75]
	v_mfma_f32_16x16x32_bf16 v[104:107], v[240:243], v[180:183], v[76:79]
	v_mfma_f32_16x16x32_bf16 v[108:111], v[244:247], v[184:187], v[108:111]
	v_mfma_f32_16x16x32_bf16 v[104:107], v[244:247], v[188:191], v[104:107]
	s_cmp_le_i32 s23, s75
	s_cbranch_scc0 .LBB0_379
.LBB0_371:
	s_waitcnt lgkmcnt(8)
	ds_read_b64_tr_b16 v[140:141], v213 offset:1024
	ds_read_b64_tr_b16 v[142:143], v213 offset:5120
	ds_read_b64_tr_b16 v[144:145], v213 offset:9216
	ds_read_b64_tr_b16 v[146:147], v213 offset:13312
	v_mfma_f32_16x16x32_bf16 v[60:63], v[120:123], v[128:131], v[60:63]
	v_max_i32_e32 v160, v84, v85
	v_max3_i32 v161, v87, v96, v97
	v_max3_i32 v160, v160, v86, v98
	v_max3_i32 v161, v161, v100, v101
	v_mfma_f32_16x16x32_bf16 v[64:67], v[124:127], v[128:131], v[64:67]
	v_max3_i32 v160, v160, v99, v102
	v_max3_i32 v161, v161, v108, v109
	v_max3_i32 v160, v160, v103, v110
	v_max3_i32 v162, v160, v111, v161
	v_mfma_f32_16x16x32_bf16 v[60:63], v[112:115], v[132:135], v[60:63]
	v_max_i32_e32 v160, v80, v81
	v_max3_i32 v161, v83, v88, v89
	v_max3_i32 v160, v160, v82, v90
	v_max3_i32 v161, v161, v92, v93
	v_mfma_f32_16x16x32_bf16 v[64:67], v[116:119], v[132:135], v[64:67]
	v_max3_i32 v160, v160, v91, v94
	v_max3_i32 v161, v161, v104, v105
	v_max3_i32 v160, v160, v95, v106
	v_max3_i32 v160, v160, v107, v161
	v_max_f32_e32 v161, v160, v160
	v_max_f32_e32 v163, v162, v162
	v_max_f32_e32 v164, v163, v161
	v_cmp_ge_f32_e32 vcc, s3, v164
	s_cmp_lg_u64 vcc, exec
	s_cselect_b64 s[12:13], -1, 0
	s_cmp_eq_u64 vcc, exec
	v_mov_b32_e32 v239, 1.0
	s_cbranch_scc0 .LBB0_383
	v_mov_b32_e32 v238, 1.0
.LBB0_373:
	s_waitcnt lgkmcnt(8)
	ds_read_b64_tr_b16 v[240:241], v212 offset:2048
	ds_read_b64_tr_b16 v[242:243], v212 offset:6144
	ds_read_b64_tr_b16 v[244:245], v212 offset:10240
	ds_read_b64_tr_b16 v[246:247], v212 offset:14336
	v_mfma_f32_16x16x32_bf16 v[52:55], v[120:123], v[136:139], v[52:55]
	v_exp_f32_e32 v162, v84
	v_mfma_f32_16x16x32_bf16 v[48:51], v[124:127], v[136:139], v[48:51]
	v_exp_f32_e32 v163, v85
	v_mfma_f32_16x16x32_bf16 v[52:55], v[112:115], v[148:151], v[52:55]
	v_exp_f32_e32 v161, v86
	v_mfma_f32_16x16x32_bf16 v[48:51], v[116:119], v[148:151], v[48:51]
	v_exp_f32_e32 v160, v87
	v_exp_f32_e32 v167, v96
	s_waitcnt lgkmcnt(8)
	ds_read_b64_tr_b16 v[128:129], v213 offset:2048
	ds_read_b64_tr_b16 v[130:131], v213 offset:6144
	ds_read_b64_tr_b16 v[132:133], v213 offset:10240
	ds_read_b64_tr_b16 v[134:135], v213 offset:14336
	v_mfma_f32_16x16x32_bf16 v[44:47], v[120:123], v[152:155], v[44:47]
	v_exp_f32_e32 v166, v97
	v_mfma_f32_16x16x32_bf16 v[40:43], v[124:127], v[152:155], v[40:43]
	v_exp_f32_e32 v164, v98
	v_mfma_f32_16x16x32_bf16 v[44:47], v[112:115], v[156:159], v[44:47]
	v_exp_f32_e32 v165, v99
	v_mfma_f32_16x16x32_bf16 v[40:43], v[116:119], v[156:159], v[40:43]
	v_exp_f32_e32 v171, v100
	v_exp_f32_e32 v170, v101
	s_waitcnt lgkmcnt(8)
	ds_read_b64_tr_b16 v[136:137], v212 offset:3072
	ds_read_b64_tr_b16 v[138:139], v212 offset:7168
	ds_read_b64_tr_b16 v[148:149], v212 offset:11264
	ds_read_b64_tr_b16 v[150:151], v212 offset:15360
	v_mfma_f32_16x16x32_bf16 v[32:35], v[120:123], v[140:143], v[32:35]
	v_exp_f32_e32 v169, v102
	v_mfma_f32_16x16x32_bf16 v[36:39], v[124:127], v[140:143], v[36:39]
	v_exp_f32_e32 v168, v103
	v_mfma_f32_16x16x32_bf16 v[32:35], v[112:115], v[144:147], v[32:35]
	v_exp_f32_e32 v178, v108
	v_mfma_f32_16x16x32_bf16 v[36:39], v[116:119], v[144:147], v[36:39]
	v_exp_f32_e32 v179, v109
	v_exp_f32_e32 v177, v110
	s_waitcnt lgkmcnt(8)
	ds_read_b64_tr_b16 v[152:153], v213 offset:3072
	ds_read_b64_tr_b16 v[154:155], v213 offset:7168
	ds_read_b64_tr_b16 v[156:157], v213 offset:11264
	ds_read_b64_tr_b16 v[158:159], v213 offset:15360
	v_mfma_f32_16x16x32_bf16 v[20:23], v[120:123], v[240:243], v[20:23]
	v_exp_f32_e32 v176, v111
	v_mfma_f32_16x16x32_bf16 v[16:19], v[124:127], v[240:243], v[16:19]
	v_exp_f32_e32 v175, v80
	v_mfma_f32_16x16x32_bf16 v[20:23], v[112:115], v[244:247], v[20:23]
	v_exp_f32_e32 v174, v81
	v_mfma_f32_16x16x32_bf16 v[16:19], v[116:119], v[244:247], v[16:19]
	v_exp_f32_e32 v172, v82
	v_exp_f32_e32 v173, v83
	s_waitcnt lgkmcnt(8)
	v_mfma_f32_16x16x32_bf16 v[28:31], v[120:123], v[128:131], v[28:31]
	v_exp_f32_e32 v183, v88
	v_mfma_f32_16x16x32_bf16 v[24:27], v[124:127], v[128:131], v[24:27]
	v_exp_f32_e32 v182, v89
	v_mfma_f32_16x16x32_bf16 v[28:31], v[112:115], v[132:135], v[28:31]
	v_exp_f32_e32 v181, v90
	v_mfma_f32_16x16x32_bf16 v[24:27], v[116:119], v[132:135], v[24:27]
	v_exp_f32_e32 v180, v91
	s_waitcnt lgkmcnt(4)
	v_mfma_f32_16x16x32_bf16 v[12:15], v[120:123], v[136:139], v[12:15]
	v_exp_f32_e32 v186, v92
	v_mfma_f32_16x16x32_bf16 v[8:11], v[124:127], v[136:139], v[8:11]
	v_exp_f32_e32 v187, v93
	v_mfma_f32_16x16x32_bf16 v[12:15], v[112:115], v[148:151], v[12:15]
	v_exp_f32_e32 v185, v94
	v_mfma_f32_16x16x32_bf16 v[8:11], v[116:119], v[148:151], v[8:11]
	v_exp_f32_e32 v184, v95
	s_waitcnt lgkmcnt(0)
	v_mfma_f32_16x16x32_bf16 v[4:7], v[120:123], v[152:155], v[4:7]
	v_exp_f32_e32 v191, v104
	v_mfma_f32_16x16x32_bf16 v[0:3], v[124:127], v[152:155], v[0:3]
	v_exp_f32_e32 v190, v105
	v_mfma_f32_16x16x32_bf16 v[4:7], v[112:115], v[156:159], v[4:7]
	v_exp_f32_e32 v189, v106
	v_mfma_f32_16x16x32_bf16 v[0:3], v[116:119], v[156:159], v[0:3]
	v_exp_f32_e32 v188, v107
	s_waitcnt vmcnt(3)
	s_waitcnt lgkmcnt(0)
	s_add_i32 s0, s23, 1
	s_cmp_ge_i32 s0, s14
	s_mov_b64 s[0:1], -1
	s_barrier
	s_cbranch_scc1 .LBB0_368
	s_and_b32 s0, s20, 0x6000
	v_add_u32_e32 v84, s0, v229
	v_add_u32_e32 v86, v84, v230
	v_add_u32_e32 v87, v84, v231
	ds_read_b128 v[240:243], v228
	ds_read_b128 v[128:131], v86
	ds_read_b128 v[244:247], v228 offset:2048
	ds_read_b128 v[132:135], v87
	ds_read_b128 v[152:155], v228 offset:1024
	ds_read_b128 v[156:159], v228 offset:3072
	ds_read_b128 v[136:139], v86 offset:512
	ds_read_b128 v[148:151], v87 offset:512
	ds_read_b128 v[140:143], v86 offset:4096
	ds_read_b128 v[144:147], v87 offset:4096
	s_min_i32 s0, s23, 0xfc
	s_add_i32 s6, s0, 3
	s_mul_i32 s0, s6, 0xc0000
	s_add_u32 s0, s86, s0
	s_addc_u32 s1, s87, 0
	s_and_b32 s6, s6, 3
	s_lshl_b32 s7, s6, 13
	s_lshl_b32 s6, s6, 14
	v_mov_b32_e32 v80, v232
	v_mov_b32_e32 v81, v234
	v_mov_b32_e32 v82, v233
	s_add_i32 m0, s17, s7
	s_add_i32 s6, s18, s6
	s_nop 0
	global_load_lds_dwordx4 v80, s[0:1]
	s_mov_b32 m0, s6
	s_nop 0
	global_load_lds_dwordx4 v82, s[0:1]
	s_add_i32 m0, s6, 0x2000
	s_nop 0
	global_load_lds_dwordx4 v81, s[0:1]
	s_lshl_b32 s0, s22, 14
	v_add_u32_e32 v214, s0, v223
	v_add_u32_e32 v215, s0, v224
	v_cvt_pk_bf16_f32 v120, v162, v163
	v_cvt_pk_bf16_f32 v121, v161, v160
	v_cvt_pk_bf16_f32 v122, v167, v166
	v_cvt_pk_bf16_f32 v123, v164, v165
	v_cvt_pk_bf16_f32 v112, v171, v170
	v_cvt_pk_bf16_f32 v113, v169, v168
	v_cvt_pk_bf16_f32 v114, v178, v179
	v_cvt_pk_bf16_f32 v115, v177, v176
	v_cvt_pk_bf16_f32 v124, v175, v174
	v_cvt_pk_bf16_f32 v125, v172, v173
	v_cvt_pk_bf16_f32 v126, v183, v182
	v_cvt_pk_bf16_f32 v127, v181, v180
	v_cvt_pk_bf16_f32 v116, v186, v187
	v_cvt_pk_bf16_f32 v117, v185, v184
	v_cvt_pk_bf16_f32 v118, v191, v190
	v_cvt_pk_bf16_f32 v119, v189, v188
	s_andn2_b64 vcc, exec, s[12:13]
	s_cbranch_vccz .Lh2a_resc
.Lh2a_resc_ret:
	s_mov_b32 s82, s80
	s_mov_b32 s83, s80
	s_mov_b32 s81, s80
	v_mov_b64_e32 v[186:187], s[82:83]
	v_mov_b64_e32 v[184:185], s[80:81]
	ds_read_b128 v[160:163], v86 offset:4608
	ds_read_b128 v[164:167], v87 offset:4608
	v_mfma_f32_16x16x32_bf16 v[68:71], v[120:123], v[184:187], v[68:71]
	v_mfma_f32_16x16x32_bf16 v[56:59], v[124:127], v[184:187], v[56:59]
	v_mfma_f32_16x16x32_bf16 v[68:71], v[112:115], v[184:187], v[68:71]
	v_mfma_f32_16x16x32_bf16 v[56:59], v[116:119], v[184:187], v[56:59]
	s_waitcnt lgkmcnt(6)
	ds_read_b64_tr_b16 v[168:169], v214
	ds_read_b64_tr_b16 v[170:171], v214 offset:4096
	ds_read_b64_tr_b16 v[172:173], v214 offset:8192
	ds_read_b64_tr_b16 v[174:175], v214 offset:12288
	v_mfma_f32_16x16x32_bf16 v[84:87], v[128:131], v[240:243], v[72:75]
	v_mfma_f32_16x16x32_bf16 v[80:83], v[128:131], v[244:247], v[76:79]
	v_mfma_f32_16x16x32_bf16 v[84:87], v[132:135], v[152:155], v[84:87]
	v_mfma_f32_16x16x32_bf16 v[80:83], v[132:135], v[156:159], v[80:83]
	s_waitcnt lgkmcnt(8)
	ds_read_b64_tr_b16 v[176:177], v215
	ds_read_b64_tr_b16 v[178:179], v215 offset:4096
	ds_read_b64_tr_b16 v[180:181], v215 offset:8192
	ds_read_b64_tr_b16 v[182:183], v215 offset:12288
	v_mfma_f32_16x16x32_bf16 v[96:99], v[136:139], v[240:243], v[72:75]
	v_mfma_f32_16x16x32_bf16 v[88:91], v[136:139], v[244:247], v[76:79]
	v_mfma_f32_16x16x32_bf16 v[96:99], v[148:151], v[152:155], v[96:99]
	v_mfma_f32_16x16x32_bf16 v[88:91], v[148:151], v[156:159], v[88:91]
	s_waitcnt lgkmcnt(10)
	ds_read_b64_tr_b16 v[184:185], v214 offset:1024
	ds_read_b64_tr_b16 v[186:187], v214 offset:5120
	ds_read_b64_tr_b16 v[188:189], v214 offset:9216
	ds_read_b64_tr_b16 v[190:191], v214 offset:13312
	v_mfma_f32_16x16x32_bf16 v[100:103], v[140:143], v[240:243], v[72:75]
	v_mfma_f32_16x16x32_bf16 v[92:95], v[140:143], v[244:247], v[76:79]
	v_mfma_f32_16x16x32_bf16 v[100:103], v[144:147], v[152:155], v[100:103]
	v_mfma_f32_16x16x32_bf16 v[92:95], v[144:147], v[156:159], v[92:95]
	s_waitcnt lgkmcnt(12)
	v_mfma_f32_16x16x32_bf16 v[108:111], v[160:163], v[240:243], v[72:75]
	v_mfma_f32_16x16x32_bf16 v[104:107], v[160:163], v[244:247], v[76:79]
	v_mfma_f32_16x16x32_bf16 v[108:111], v[164:167], v[152:155], v[108:111]
	v_mfma_f32_16x16x32_bf16 v[104:107], v[164:167], v[156:159], v[104:107]
	s_cmp_lt_i32 s23, s75
	s_cbranch_scc0 .LBB0_384
.LBB0_376:
	s_waitcnt lgkmcnt(8)
	ds_read_b64_tr_b16 v[140:141], v215 offset:1024
	ds_read_b64_tr_b16 v[142:143], v215 offset:5120
	ds_read_b64_tr_b16 v[144:145], v215 offset:9216
	ds_read_b64_tr_b16 v[146:147], v215 offset:13312
	v_mfma_f32_16x16x32_bf16 v[60:63], v[120:123], v[168:171], v[60:63]
	v_max_i32_e32 v240, v84, v85
	v_max3_i32 v241, v87, v96, v97
	v_max3_i32 v240, v240, v86, v98
	v_max3_i32 v241, v241, v100, v101
	v_mfma_f32_16x16x32_bf16 v[64:67], v[124:127], v[168:171], v[64:67]
	v_max3_i32 v240, v240, v99, v102
	v_max3_i32 v241, v241, v108, v109
	v_max3_i32 v240, v240, v103, v110
	v_max3_i32 v242, v240, v111, v241
	v_mfma_f32_16x16x32_bf16 v[60:63], v[112:115], v[172:175], v[60:63]
	v_max_i32_e32 v240, v80, v81
	v_max3_i32 v241, v83, v88, v89
	v_max3_i32 v240, v240, v82, v90
	v_max3_i32 v241, v241, v92, v93
	v_mfma_f32_16x16x32_bf16 v[64:67], v[116:119], v[172:175], v[64:67]
	v_max3_i32 v240, v240, v91, v94
	v_max3_i32 v241, v241, v104, v105
	v_max3_i32 v240, v240, v95, v106
	v_max3_i32 v241, v240, v107, v241
	v_max_f32_e32 v240, v241, v241
	v_max_f32_e32 v243, v242, v242
	v_max_f32_e32 v212, v243, v240
	v_cmp_ge_f32_e32 vcc, s3, v212
	s_cmp_lg_u64 vcc, exec
	s_cselect_b64 s[6:7], -1, 0
	s_mov_b64 vcc, s[6:7]
	s_cbranch_vccnz .LBB0_388
	v_mov_b32_e32 v249, 1.0
	s_cbranch_execnz .LBB0_389

.LBB0_379:
	v_cmp_gt_i32_e32 vcc, s23, v235
	v_mov_b32_e32 v240, 0xf149f2ca
	v_cmp_gt_i32_e64 s[0:1], s23, v236
	v_cndmask_b32_e32 v84, v84, v240, vcc
	v_cndmask_b32_e32 v85, v85, v240, vcc
	v_cndmask_b32_e64 v80, v80, v240, s[0:1]
	v_cndmask_b32_e64 v81, v81, v240, s[0:1]
	v_cndmask_b32_e32 v86, v86, v240, vcc
	v_cndmask_b32_e64 v82, v82, v240, s[0:1]
	v_cndmask_b32_e32 v87, v87, v240, vcc
	v_cndmask_b32_e64 v83, v83, v240, s[0:1]
	v_cndmask_b32_e32 v96, v96, v240, vcc
	v_cndmask_b32_e64 v88, v88, v240, s[0:1]
	v_cndmask_b32_e32 v97, v97, v240, vcc
	v_cndmask_b32_e64 v89, v89, v240, s[0:1]
	v_cndmask_b32_e32 v98, v98, v240, vcc
	v_cndmask_b32_e64 v90, v90, v240, s[0:1]
	v_cndmask_b32_e32 v99, v99, v240, vcc
	v_cndmask_b32_e64 v91, v91, v240, s[0:1]
	v_cndmask_b32_e32 v100, v100, v240, vcc
	v_cndmask_b32_e64 v92, v92, v240, s[0:1]
	v_cndmask_b32_e32 v101, v101, v240, vcc
	v_cndmask_b32_e64 v93, v93, v240, s[0:1]
	v_cndmask_b32_e32 v102, v102, v240, vcc
	v_cndmask_b32_e64 v94, v94, v240, s[0:1]
	v_cndmask_b32_e32 v103, v103, v240, vcc
	v_cndmask_b32_e64 v95, v95, v240, s[0:1]
	v_cndmask_b32_e32 v108, v108, v240, vcc
	v_cndmask_b32_e64 v104, v104, v240, s[0:1]
	v_cndmask_b32_e32 v109, v109, v240, vcc
	v_cndmask_b32_e64 v105, v105, v240, s[0:1]
	v_cndmask_b32_e32 v110, v110, v240, vcc
	v_cndmask_b32_e64 v106, v106, v240, s[0:1]
	v_cndmask_b32_e32 v111, v111, v240, vcc
	v_cndmask_b32_e64 v107, v107, v240, s[0:1]
	s_branch .LBB0_371

.LBB0_384:
	v_cmp_lt_i32_e32 vcc, s23, v235
	v_mov_b32_e32 v160, 0xf149f2ca
	v_cmp_lt_i32_e64 s[0:1], s23, v236
	v_cndmask_b32_e32 v84, v160, v84, vcc
	v_cndmask_b32_e32 v85, v160, v85, vcc
	v_cndmask_b32_e64 v80, v160, v80, s[0:1]
	v_cndmask_b32_e64 v81, v160, v81, s[0:1]
	v_cndmask_b32_e32 v86, v160, v86, vcc
	v_cndmask_b32_e64 v82, v160, v82, s[0:1]
	v_cndmask_b32_e32 v87, v160, v87, vcc
	v_cndmask_b32_e64 v83, v160, v83, s[0:1]
	v_cndmask_b32_e32 v96, v160, v96, vcc
	v_cndmask_b32_e64 v88, v160, v88, s[0:1]
	v_cndmask_b32_e32 v97, v160, v97, vcc
	v_cndmask_b32_e64 v89, v160, v89, s[0:1]
	v_cndmask_b32_e32 v98, v160, v98, vcc
	v_cndmask_b32_e64 v90, v160, v90, s[0:1]
	v_cndmask_b32_e32 v99, v160, v99, vcc
	v_cndmask_b32_e64 v91, v160, v91, s[0:1]
	v_cndmask_b32_e32 v100, v160, v100, vcc
	v_cndmask_b32_e64 v92, v160, v92, s[0:1]
	v_cndmask_b32_e32 v101, v160, v101, vcc
	v_cndmask_b32_e64 v93, v160, v93, s[0:1]
	v_cndmask_b32_e32 v102, v160, v102, vcc
	v_cndmask_b32_e64 v94, v160, v94, s[0:1]
	v_cndmask_b32_e32 v103, v160, v103, vcc
	v_cndmask_b32_e64 v95, v160, v95, s[0:1]
	v_cndmask_b32_e32 v108, v160, v108, vcc
	v_cndmask_b32_e64 v104, v160, v104, s[0:1]
	v_cndmask_b32_e32 v109, v160, v109, vcc
	v_cndmask_b32_e64 v105, v160, v105, s[0:1]
	v_cndmask_b32_e32 v110, v160, v110, vcc
	v_cndmask_b32_e64 v106, v160, v106, s[0:1]
	v_cndmask_b32_e32 v111, v160, v111, vcc
	v_cndmask_b32_e64 v107, v160, v107, s[0:1]
	s_branch .LBB0_376
.Lh2a_resc:
	s_and_saveexec_b64 s[0:1], s[4:5]
	ds_write2_b32 v237, v238, v239 offset0:32 offset1:48
	s_or_b64 exec, exec, s[0:1]
	s_waitcnt lgkmcnt(0)
	v_add_u32_e32 v172, v225, v192
	ds_read_b128 v[168:171], v172 offset:128
	s_waitcnt lgkmcnt(0)
	v_pk_mul_f32 v[70:71], v[70:71], v[170:171]
	v_pk_mul_f32 v[68:69], v[68:69], v[168:169]
	v_pk_mul_f32 v[62:63], v[62:63], v[170:171]
	v_pk_mul_f32 v[60:61], v[60:61], v[168:169]
	v_pk_mul_f32 v[54:55], v[54:55], v[170:171]
	v_pk_mul_f32 v[52:53], v[52:53], v[168:169]
	v_pk_mul_f32 v[46:47], v[46:47], v[170:171]
	v_pk_mul_f32 v[44:45], v[44:45], v[168:169]
	v_pk_mul_f32 v[34:35], v[34:35], v[170:171]
	v_pk_mul_f32 v[32:33], v[32:33], v[168:169]
	v_pk_mul_f32 v[22:23], v[22:23], v[170:171]
	v_pk_mul_f32 v[20:21], v[20:21], v[168:169]
	v_pk_mul_f32 v[30:31], v[30:31], v[170:171]
	v_pk_mul_f32 v[28:29], v[28:29], v[168:169]
	v_pk_mul_f32 v[14:15], v[14:15], v[170:171]
	v_pk_mul_f32 v[12:13], v[12:13], v[168:169]
	v_pk_mul_f32 v[6:7], v[6:7], v[170:171]
	v_pk_mul_f32 v[4:5], v[4:5], v[168:169]
	ds_read_b128 v[168:171], v172 offset:192
	s_waitcnt lgkmcnt(0)
	v_pk_mul_f32 v[58:59], v[58:59], v[170:171]
	v_pk_mul_f32 v[56:57], v[56:57], v[168:169]
	v_pk_mul_f32 v[66:67], v[66:67], v[170:171]
	v_pk_mul_f32 v[64:65], v[64:65], v[168:169]
	v_pk_mul_f32 v[50:51], v[50:51], v[170:171]
	v_pk_mul_f32 v[48:49], v[48:49], v[168:169]
	v_pk_mul_f32 v[42:43], v[42:43], v[170:171]
	v_pk_mul_f32 v[40:41], v[40:41], v[168:169]
	v_pk_mul_f32 v[38:39], v[38:39], v[170:171]
	v_pk_mul_f32 v[36:37], v[36:37], v[168:169]
	v_pk_mul_f32 v[18:19], v[18:19], v[170:171]
	v_pk_mul_f32 v[16:17], v[16:17], v[168:169]
	v_pk_mul_f32 v[26:27], v[26:27], v[170:171]
	v_pk_mul_f32 v[24:25], v[24:25], v[168:169]
	v_pk_mul_f32 v[10:11], v[10:11], v[170:171]
	v_pk_mul_f32 v[8:9], v[8:9], v[168:169]
	v_pk_mul_f32 v[2:3], v[2:3], v[170:171]
	v_pk_mul_f32 v[0:1], v[0:1], v[168:169]
	s_branch .Lh2a_resc_ret

; #define VWAIT(n) asm volatile("s_waitcnt vmcnt(" #n ")" ::: "memory")
; #define LBAR() do { asm volatile("s_waitcnt lgkmcnt(0)" ::: "memory"); __builtin_amdgcn_s_barrier(); } while (0)
; #define VWAIT(n) asm volatile("s_waitcnt vmcnt(" #n ")" ::: "memory")
; #define LBAR() do { asm volatile("s_waitcnt lgkmcnt(0)" ::: "memory"); __builtin_amdgcn_s_barrier(); } while (0)
; #define ROWMAXF16(S, pm) do { _Pragma("unroll") for (int g = 0; g < 2; ++g) { float m_ = S[g][0][0]; \
;       _Pragma("unroll") for (int kb = 0; kb < 4; ++kb) _Pragma("unroll") for (int j = 0; j < 4; ++j) m_ = fmaxf(m_, S[g][kb][j]); pm[g] = m_; } } while (0)
; #define EXP16(S) do { _Pragma("unroll") for (int g = 0; g < 2; ++g) _Pragma("unroll") for (int kb = 0; kb < 4; ++kb) _Pragma("unroll") for (int j = 0; j < 4; ++j) S[g][kb][j] = __builtin_amdgcn_exp2f(S[g][kb][j]); } while (0)
; DEV void diff16_pass(const bf16_t* __restrict__ proj, int qcol, int kcol, int vcol, int q0, f32x4 (&o)[2][8], f32x4 (&l_out)[2], unsigned char* lds) {
;     ...
;   float m_reg[2] = {0.f, 0.f};
;   f32x4 ol[2] = {(f32x4){0.f, 0.f, 0.f, 0.f}, (f32x4){0.f, 0.f, 0.f, 0.f}};
;   const bf16x8 ones = {0x3F80, 0x3F80, 0x3F80, 0x3F80, 0x3F80, 0x3F80, 0x3F80, 0x3F80};
;   f32x4 negm[2] = {(f32x4){0.f, 0.f, 0.f, 0.f}, (f32x4){0.f, 0.f, 0.f, 0.f}};
; #pragma unroll
;   for (int g = 0; g < 2; ++g)
; #pragma unroll
;     for (int cb = 0; cb < 8; ++cb) o[g][cb] = (f32x4){0.f, 0.f, 0.f, 0.f};
;   f32x4 SA[2][4], SB2[2][4]; float alA[2], alB[2]; bool rfA = false, rfB = false; bf16x8 pa[2][2];
;   DMA(0); DMA(1); DMA(2); VWAIT(3); LBAR();
;   { QKT16(SA, 0); float pm_[2]; ROWMAXF16(SA, pm_); RESCALE16(SA, pm_, alA, rfA, true); alA[0] = 1.f; alA[1] = 1.f; rfA = false; EXP16(SA); }
;   for (int j = 1; j < NT; j += 2) {
;     HALF16(SB2, alB, rfB, SA, alA, rfA, j);
;     if (j + 1 >= NT) break;
;     HALF16(SA, alA, rfA, SB2, alB, rfB, j + 1);
;   }
.LBB0_390:
	s_waitcnt lgkmcnt(8)
	ds_read_b64_tr_b16 v[160:161], v214 offset:2048
	ds_read_b64_tr_b16 v[162:163], v214 offset:6144
	ds_read_b64_tr_b16 v[164:165], v214 offset:10240
	ds_read_b64_tr_b16 v[166:167], v214 offset:14336
	v_mfma_f32_16x16x32_bf16 v[52:55], v[120:123], v[176:179], v[52:55]
	v_exp_f32_e32 v241, v84
	v_mfma_f32_16x16x32_bf16 v[48:51], v[124:127], v[176:179], v[48:51]
	v_exp_f32_e32 v244, v85
	v_mfma_f32_16x16x32_bf16 v[52:55], v[112:115], v[180:183], v[52:55]
	v_exp_f32_e32 v245, v86
	v_mfma_f32_16x16x32_bf16 v[48:51], v[116:119], v[180:183], v[48:51]
	v_exp_f32_e32 v247, v87
	v_exp_f32_e32 v240, v96
	s_waitcnt lgkmcnt(8)
	ds_read_b64_tr_b16 v[168:169], v215 offset:2048
	ds_read_b64_tr_b16 v[170:171], v215 offset:6144
	ds_read_b64_tr_b16 v[172:173], v215 offset:10240
	ds_read_b64_tr_b16 v[174:175], v215 offset:14336
	v_mfma_f32_16x16x32_bf16 v[44:47], v[120:123], v[184:187], v[44:47]
	v_exp_f32_e32 v242, v97
	v_mfma_f32_16x16x32_bf16 v[40:43], v[124:127], v[184:187], v[40:43]
	v_exp_f32_e32 v243, v98
	v_mfma_f32_16x16x32_bf16 v[44:47], v[112:115], v[188:191], v[44:47]
	v_exp_f32_e32 v246, v99
	v_mfma_f32_16x16x32_bf16 v[40:43], v[116:119], v[188:191], v[40:43]
	v_exp_f32_e32 v137, v80
	v_exp_f32_e32 v148, v81
	s_waitcnt lgkmcnt(8)
	ds_read_b64_tr_b16 v[176:177], v214 offset:3072
	ds_read_b64_tr_b16 v[178:179], v214 offset:7168
	ds_read_b64_tr_b16 v[180:181], v214 offset:11264
	ds_read_b64_tr_b16 v[182:183], v214 offset:15360
	v_mfma_f32_16x16x32_bf16 v[32:35], v[120:123], v[140:143], v[32:35]
	v_exp_f32_e32 v149, v82
	v_mfma_f32_16x16x32_bf16 v[36:39], v[124:127], v[140:143], v[36:39]
	v_exp_f32_e32 v151, v83
	v_mfma_f32_16x16x32_bf16 v[32:35], v[112:115], v[144:147], v[32:35]
	v_exp_f32_e32 v136, v89
	v_mfma_f32_16x16x32_bf16 v[36:39], v[116:119], v[144:147], v[36:39]
	v_exp_f32_e32 v139, v90
	v_exp_f32_e32 v150, v91
	s_waitcnt lgkmcnt(8)
	ds_read_b64_tr_b16 v[184:185], v215 offset:3072
	ds_read_b64_tr_b16 v[186:187], v215 offset:7168
	ds_read_b64_tr_b16 v[188:189], v215 offset:11264
	ds_read_b64_tr_b16 v[190:191], v215 offset:15360
	v_mfma_f32_16x16x32_bf16 v[20:23], v[120:123], v[160:163], v[20:23]
	v_exp_f32_e32 v129, v92
	v_mfma_f32_16x16x32_bf16 v[16:19], v[124:127], v[160:163], v[16:19]
	v_exp_f32_e32 v138, v95
	v_mfma_f32_16x16x32_bf16 v[20:23], v[112:115], v[164:167], v[20:23]
	v_exp_f32_e32 v128, v104
	v_mfma_f32_16x16x32_bf16 v[16:19], v[116:119], v[164:167], v[16:19]
	v_exp_f32_e32 v130, v105
	v_exp_f32_e32 v131, v106
	s_waitcnt lgkmcnt(8)
	v_mfma_f32_16x16x32_bf16 v[28:31], v[120:123], v[168:171], v[28:31]
	v_exp_f32_e32 v153, v100
	v_mfma_f32_16x16x32_bf16 v[24:27], v[124:127], v[168:171], v[24:27]
	v_exp_f32_e32 v152, v108
	v_mfma_f32_16x16x32_bf16 v[28:31], v[112:115], v[172:175], v[28:31]
	v_exp_f32_e32 v154, v109
	v_mfma_f32_16x16x32_bf16 v[24:27], v[116:119], v[172:175], v[24:27]
	v_exp_f32_e32 v155, v110
	s_waitcnt lgkmcnt(4)
	v_mfma_f32_16x16x32_bf16 v[12:15], v[120:123], v[176:179], v[12:15]
	v_exp_f32_e32 v156, v101
	v_mfma_f32_16x16x32_bf16 v[8:11], v[124:127], v[176:179], v[8:11]
	v_exp_f32_e32 v158, v102
	v_mfma_f32_16x16x32_bf16 v[12:15], v[112:115], v[180:183], v[12:15]
	v_exp_f32_e32 v159, v103
	v_mfma_f32_16x16x32_bf16 v[8:11], v[116:119], v[180:183], v[8:11]
	v_exp_f32_e32 v157, v111
	s_waitcnt lgkmcnt(0)
	v_mfma_f32_16x16x32_bf16 v[4:7], v[120:123], v[184:187], v[4:7]
	v_exp_f32_e32 v132, v88
	v_mfma_f32_16x16x32_bf16 v[0:3], v[124:127], v[184:187], v[0:3]
	v_exp_f32_e32 v134, v93
	v_mfma_f32_16x16x32_bf16 v[4:7], v[112:115], v[188:191], v[4:7]
	v_exp_f32_e32 v135, v94
	v_mfma_f32_16x16x32_bf16 v[0:3], v[116:119], v[188:191], v[0:3]
	v_exp_f32_e32 v133, v107
	s_waitcnt vmcnt(3)
	s_waitcnt lgkmcnt(0)
	s_add_i32 s19, s19, 0x8000
	s_addk_i32 s20, 0x4000
	s_cmp_ge_i32 s21, s14
	s_cselect_b64 s[0:1], -1, 0
	s_barrier
	s_and_b64 vcc, exec, s[0:1]
	s_mov_b32 s23, s21
	s_cbranch_vccz .LBB0_369
	s_branch .LBB0_392

.LBB0_396:
	s_and_b32 s18, s19, 3
	v_lshl_add_u32 v84, s18, 13, v229
	v_add_u32_e32 v86, v84, v230
	v_add_u32_e32 v87, v84, v231
	ds_read_b128 v[176:179], v228
	ds_read_b128 v[160:163], v86
	ds_read_b128 v[180:183], v228 offset:2048
	ds_read_b128 v[164:167], v87
	ds_read_b128 v[184:187], v228 offset:1024
	ds_read_b128 v[188:191], v228 offset:3072
	ds_read_b128 v[168:171], v86 offset:512
	ds_read_b128 v[172:175], v87 offset:512
	ds_read_b128 v[140:143], v86 offset:4096
	ds_read_b128 v[144:147], v87 offset:4096
	s_add_i32 s17, s19, 2
	s_min_i32 s10, s17, 0xff
	s_mul_i32 s0, s10, 0xc0000
	s_add_u32 s0, s86, s0
	s_addc_u32 s1, s87, 0
	s_and_b32 s10, s10, 3
	s_lshl_b32 s11, s10, 13
	s_lshl_b32 s10, s10, 14
	v_mov_b32_e32 v80, v234
	v_mov_b32_e32 v81, v233
	v_mov_b32_e32 v82, v232
	s_add_i32 m0, s12, s11
	s_add_i32 s10, s13, s10
	s_nop 0
	global_load_lds_dwordx4 v82, s[0:1]
	s_mov_b32 m0, s10
	s_nop 0
	global_load_lds_dwordx4 v81, s[0:1]
	s_add_i32 m0, s10, 0x2000
	s_nop 0
	global_load_lds_dwordx4 v80, s[0:1]
	s_and_b32 s0, s15, 0xc000
	v_add_u32_e32 v212, s0, v223
	v_add_u32_e32 v213, s0, v224
	v_cvt_pk_bf16_f32 v120, v241, v244
	v_cvt_pk_bf16_f32 v121, v245, v247
	v_cvt_pk_bf16_f32 v122, v240, v242
	v_cvt_pk_bf16_f32 v123, v243, v246
	v_cvt_pk_bf16_f32 v112, v153, v156
	v_cvt_pk_bf16_f32 v113, v158, v159
	v_cvt_pk_bf16_f32 v114, v152, v154
	v_cvt_pk_bf16_f32 v115, v155, v157
	v_cvt_pk_bf16_f32 v124, v137, v148
	v_cvt_pk_bf16_f32 v125, v149, v151
	v_cvt_pk_bf16_f32 v126, v132, v136
	v_cvt_pk_bf16_f32 v127, v139, v150
	v_cvt_pk_bf16_f32 v116, v129, v134
	v_cvt_pk_bf16_f32 v117, v135, v138
	v_cvt_pk_bf16_f32 v118, v128, v130
	v_cvt_pk_bf16_f32 v119, v131, v133
	s_andn2_b64 vcc, exec, s[6:7]
	s_cbranch_vccz .Lh1b_resc
.Lh1b_resc_ret:
	s_mov_b32 s82, s80
	s_mov_b32 s83, s80
	s_mov_b32 s81, s80
	v_mov_b64_e32 v[154:155], s[82:83]
	v_mov_b64_e32 v[152:153], s[80:81]
	ds_read_b128 v[240:243], v86 offset:4608
	ds_read_b128 v[244:247], v87 offset:4608
	v_mfma_f32_16x16x32_bf16 v[68:71], v[120:123], v[152:155], v[68:71]
	v_mfma_f32_16x16x32_bf16 v[56:59], v[124:127], v[152:155], v[56:59]
	v_mfma_f32_16x16x32_bf16 v[68:71], v[112:115], v[152:155], v[68:71]
	v_mfma_f32_16x16x32_bf16 v[56:59], v[116:119], v[152:155], v[56:59]
	s_waitcnt lgkmcnt(6)
	ds_read_b64_tr_b16 v[128:129], v212
	ds_read_b64_tr_b16 v[130:131], v212 offset:4096
	ds_read_b64_tr_b16 v[132:133], v212 offset:8192
	ds_read_b64_tr_b16 v[134:135], v212 offset:12288
	v_mfma_f32_16x16x32_bf16 v[84:87], v[160:163], v[176:179], v[72:75]
	v_mfma_f32_16x16x32_bf16 v[80:83], v[160:163], v[180:183], v[76:79]
	v_mfma_f32_16x16x32_bf16 v[84:87], v[164:167], v[184:187], v[84:87]
	v_mfma_f32_16x16x32_bf16 v[80:83], v[164:167], v[188:191], v[80:83]
	s_waitcnt lgkmcnt(8)
	ds_read_b64_tr_b16 v[136:137], v213
	ds_read_b64_tr_b16 v[138:139], v213 offset:4096
	ds_read_b64_tr_b16 v[148:149], v213 offset:8192
	ds_read_b64_tr_b16 v[150:151], v213 offset:12288
	v_mfma_f32_16x16x32_bf16 v[96:99], v[168:171], v[176:179], v[72:75]
	v_mfma_f32_16x16x32_bf16 v[88:91], v[168:171], v[180:183], v[76:79]
	v_mfma_f32_16x16x32_bf16 v[96:99], v[172:175], v[184:187], v[96:99]
	v_mfma_f32_16x16x32_bf16 v[88:91], v[172:175], v[188:191], v[88:91]
	s_waitcnt lgkmcnt(10)
	ds_read_b64_tr_b16 v[152:153], v212 offset:1024
	ds_read_b64_tr_b16 v[154:155], v212 offset:5120
	ds_read_b64_tr_b16 v[156:157], v212 offset:9216
	ds_read_b64_tr_b16 v[158:159], v212 offset:13312
	v_mfma_f32_16x16x32_bf16 v[100:103], v[140:143], v[176:179], v[72:75]
	v_mfma_f32_16x16x32_bf16 v[92:95], v[140:143], v[180:183], v[76:79]
	v_mfma_f32_16x16x32_bf16 v[100:103], v[144:147], v[184:187], v[100:103]
	v_mfma_f32_16x16x32_bf16 v[92:95], v[144:147], v[188:191], v[92:95]
	s_waitcnt lgkmcnt(12)
	v_mfma_f32_16x16x32_bf16 v[108:111], v[240:243], v[176:179], v[72:75]
	v_mfma_f32_16x16x32_bf16 v[104:107], v[240:243], v[180:183], v[76:79]
	v_mfma_f32_16x16x32_bf16 v[108:111], v[244:247], v[184:187], v[108:111]
	v_mfma_f32_16x16x32_bf16 v[104:107], v[244:247], v[188:191], v[104:107]
	s_cmp_le_i32 s19, s75
	s_cbranch_scc0 .LBB0_406
.LBB0_398:
	s_waitcnt lgkmcnt(8)
	ds_read_b64_tr_b16 v[140:141], v213 offset:1024
	ds_read_b64_tr_b16 v[142:143], v213 offset:5120
	ds_read_b64_tr_b16 v[144:145], v213 offset:9216
	ds_read_b64_tr_b16 v[146:147], v213 offset:13312
	v_mfma_f32_16x16x32_bf16 v[60:63], v[120:123], v[128:131], v[60:63]
	v_max_i32_e32 v160, v84, v85
	v_max3_i32 v161, v87, v96, v97
	v_max3_i32 v160, v160, v86, v98
	v_max3_i32 v161, v161, v100, v101
	v_mfma_f32_16x16x32_bf16 v[64:67], v[124:127], v[128:131], v[64:67]
	v_max3_i32 v160, v160, v99, v102
	v_max3_i32 v161, v161, v108, v109
	v_max3_i32 v160, v160, v103, v110
	v_max3_i32 v162, v160, v111, v161
	v_mfma_f32_16x16x32_bf16 v[60:63], v[112:115], v[132:135], v[60:63]
	v_max_i32_e32 v160, v80, v81
	v_max3_i32 v161, v83, v88, v89
	v_max3_i32 v160, v160, v82, v90
	v_max3_i32 v161, v161, v92, v93
	v_mfma_f32_16x16x32_bf16 v[64:67], v[116:119], v[132:135], v[64:67]
	v_max3_i32 v160, v160, v91, v94
	v_max3_i32 v161, v161, v104, v105
	v_max3_i32 v160, v160, v95, v106
	v_max3_i32 v160, v160, v107, v161
	v_max_f32_e32 v161, v160, v160
	v_max_f32_e32 v163, v162, v162
	v_max_f32_e32 v164, v163, v161
	v_cmp_ge_f32_e32 vcc, s3, v164
	s_cmp_lg_u64 vcc, exec
	s_cselect_b64 s[10:11], -1, 0
	s_cmp_eq_u64 vcc, exec
	v_mov_b32_e32 v239, 1.0
	s_cbranch_scc0 .LBB0_410
	v_mov_b32_e32 v238, 1.0
.LBB0_400:
	s_waitcnt lgkmcnt(8)
	ds_read_b64_tr_b16 v[240:241], v212 offset:2048
	ds_read_b64_tr_b16 v[242:243], v212 offset:6144
	ds_read_b64_tr_b16 v[244:245], v212 offset:10240
	ds_read_b64_tr_b16 v[246:247], v212 offset:14336
	v_mfma_f32_16x16x32_bf16 v[52:55], v[120:123], v[136:139], v[52:55]
	v_exp_f32_e32 v162, v84
	v_mfma_f32_16x16x32_bf16 v[48:51], v[124:127], v[136:139], v[48:51]
	v_exp_f32_e32 v163, v85
	v_mfma_f32_16x16x32_bf16 v[52:55], v[112:115], v[148:151], v[52:55]
	v_exp_f32_e32 v161, v86
	v_mfma_f32_16x16x32_bf16 v[48:51], v[116:119], v[148:151], v[48:51]
	v_exp_f32_e32 v160, v87
	v_exp_f32_e32 v167, v96
	s_waitcnt lgkmcnt(8)
	ds_read_b64_tr_b16 v[128:129], v213 offset:2048
	ds_read_b64_tr_b16 v[130:131], v213 offset:6144
	ds_read_b64_tr_b16 v[132:133], v213 offset:10240
	ds_read_b64_tr_b16 v[134:135], v213 offset:14336
	v_mfma_f32_16x16x32_bf16 v[44:47], v[120:123], v[152:155], v[44:47]
	v_exp_f32_e32 v166, v97
	v_mfma_f32_16x16x32_bf16 v[40:43], v[124:127], v[152:155], v[40:43]
	v_exp_f32_e32 v164, v98
	v_mfma_f32_16x16x32_bf16 v[44:47], v[112:115], v[156:159], v[44:47]
	v_exp_f32_e32 v165, v99
	v_mfma_f32_16x16x32_bf16 v[40:43], v[116:119], v[156:159], v[40:43]
	v_exp_f32_e32 v171, v100
	v_exp_f32_e32 v170, v101
	s_waitcnt lgkmcnt(8)
	ds_read_b64_tr_b16 v[136:137], v212 offset:3072
	ds_read_b64_tr_b16 v[138:139], v212 offset:7168
	ds_read_b64_tr_b16 v[148:149], v212 offset:11264
	ds_read_b64_tr_b16 v[150:151], v212 offset:15360
	v_mfma_f32_16x16x32_bf16 v[32:35], v[120:123], v[140:143], v[32:35]
	v_exp_f32_e32 v169, v102
	v_mfma_f32_16x16x32_bf16 v[36:39], v[124:127], v[140:143], v[36:39]
	v_exp_f32_e32 v168, v103
	v_mfma_f32_16x16x32_bf16 v[32:35], v[112:115], v[144:147], v[32:35]
	v_exp_f32_e32 v178, v108
	v_mfma_f32_16x16x32_bf16 v[36:39], v[116:119], v[144:147], v[36:39]
	v_exp_f32_e32 v179, v109
	v_exp_f32_e32 v177, v110
	s_waitcnt lgkmcnt(8)
	ds_read_b64_tr_b16 v[152:153], v213 offset:3072
	ds_read_b64_tr_b16 v[154:155], v213 offset:7168
	ds_read_b64_tr_b16 v[156:157], v213 offset:11264
	ds_read_b64_tr_b16 v[158:159], v213 offset:15360
	v_mfma_f32_16x16x32_bf16 v[20:23], v[120:123], v[240:243], v[20:23]
	v_exp_f32_e32 v176, v111
	v_mfma_f32_16x16x32_bf16 v[16:19], v[124:127], v[240:243], v[16:19]
	v_exp_f32_e32 v175, v80
	v_mfma_f32_16x16x32_bf16 v[20:23], v[112:115], v[244:247], v[20:23]
	v_exp_f32_e32 v174, v81
	v_mfma_f32_16x16x32_bf16 v[16:19], v[116:119], v[244:247], v[16:19]
	v_exp_f32_e32 v172, v82
	v_exp_f32_e32 v173, v83
	s_waitcnt lgkmcnt(8)
	v_mfma_f32_16x16x32_bf16 v[28:31], v[120:123], v[128:131], v[28:31]
	v_exp_f32_e32 v183, v88
	v_mfma_f32_16x16x32_bf16 v[24:27], v[124:127], v[128:131], v[24:27]
	v_exp_f32_e32 v182, v89
	v_mfma_f32_16x16x32_bf16 v[28:31], v[112:115], v[132:135], v[28:31]
	v_exp_f32_e32 v181, v90
	v_mfma_f32_16x16x32_bf16 v[24:27], v[116:119], v[132:135], v[24:27]
	v_exp_f32_e32 v180, v91
	s_waitcnt lgkmcnt(4)
	v_mfma_f32_16x16x32_bf16 v[12:15], v[120:123], v[136:139], v[12:15]
	v_exp_f32_e32 v186, v92
	v_mfma_f32_16x16x32_bf16 v[8:11], v[124:127], v[136:139], v[8:11]
	v_exp_f32_e32 v187, v93
	v_mfma_f32_16x16x32_bf16 v[12:15], v[112:115], v[148:151], v[12:15]
	v_exp_f32_e32 v185, v94
	v_mfma_f32_16x16x32_bf16 v[8:11], v[116:119], v[148:151], v[8:11]
	v_exp_f32_e32 v184, v95
	s_waitcnt lgkmcnt(0)
	v_mfma_f32_16x16x32_bf16 v[4:7], v[120:123], v[152:155], v[4:7]
	v_exp_f32_e32 v191, v104
	v_mfma_f32_16x16x32_bf16 v[0:3], v[124:127], v[152:155], v[0:3]
	v_exp_f32_e32 v190, v105
	v_mfma_f32_16x16x32_bf16 v[4:7], v[112:115], v[156:159], v[4:7]
	v_exp_f32_e32 v189, v106
	v_mfma_f32_16x16x32_bf16 v[0:3], v[116:119], v[156:159], v[0:3]
	v_exp_f32_e32 v188, v107
	s_waitcnt vmcnt(3)
	s_waitcnt lgkmcnt(0)
	s_add_i32 s0, s19, 1
	s_cmp_ge_i32 s0, s14
	s_mov_b64 s[0:1], -1
	s_barrier
	s_cbranch_scc1 .LBB0_395
	s_and_b32 s0, s16, 0x6000
	v_add_u32_e32 v84, s0, v229
	v_add_u32_e32 v86, v84, v230
	v_add_u32_e32 v87, v84, v231
	ds_read_b128 v[240:243], v228
	ds_read_b128 v[128:131], v86
	ds_read_b128 v[244:247], v228 offset:2048
	ds_read_b128 v[132:135], v87
	ds_read_b128 v[152:155], v228 offset:1024
	ds_read_b128 v[156:159], v228 offset:3072
	ds_read_b128 v[136:139], v86 offset:512
	ds_read_b128 v[148:151], v87 offset:512
	ds_read_b128 v[140:143], v86 offset:4096
	ds_read_b128 v[144:147], v87 offset:4096
	s_min_i32 s0, s19, 0xfc
	s_add_i32 s6, s0, 3
	s_mul_i32 s0, s6, 0xc0000
	s_add_u32 s0, s86, s0
	s_addc_u32 s1, s87, 0
	s_and_b32 s6, s6, 3
	s_lshl_b32 s7, s6, 13
	s_lshl_b32 s6, s6, 14
	v_mov_b32_e32 v80, v233
	v_mov_b32_e32 v81, v232
	v_mov_b32_e32 v82, v234
	s_add_i32 m0, s12, s7
	s_add_i32 s6, s13, s6
	s_nop 0
	global_load_lds_dwordx4 v81, s[0:1]
	s_mov_b32 m0, s6
	s_nop 0
	global_load_lds_dwordx4 v80, s[0:1]
	s_add_i32 m0, s6, 0x2000
	s_nop 0
	global_load_lds_dwordx4 v82, s[0:1]
	s_lshl_b32 s0, s18, 14
	v_add_u32_e32 v214, s0, v223
	v_add_u32_e32 v215, s0, v224
	v_cvt_pk_bf16_f32 v120, v162, v163
	v_cvt_pk_bf16_f32 v121, v161, v160
	v_cvt_pk_bf16_f32 v122, v167, v166
	v_cvt_pk_bf16_f32 v123, v164, v165
	v_cvt_pk_bf16_f32 v112, v171, v170
	v_cvt_pk_bf16_f32 v113, v169, v168
	v_cvt_pk_bf16_f32 v114, v178, v179
	v_cvt_pk_bf16_f32 v115, v177, v176
	v_cvt_pk_bf16_f32 v124, v175, v174
	v_cvt_pk_bf16_f32 v125, v172, v173
	v_cvt_pk_bf16_f32 v126, v183, v182
	v_cvt_pk_bf16_f32 v127, v181, v180
	v_cvt_pk_bf16_f32 v116, v186, v187
	v_cvt_pk_bf16_f32 v117, v185, v184
	v_cvt_pk_bf16_f32 v118, v191, v190
	v_cvt_pk_bf16_f32 v119, v189, v188
	s_andn2_b64 vcc, exec, s[10:11]
	s_cbranch_vccz .Lh2b_resc
.Lh2b_resc_ret:
	s_mov_b32 s82, s80
	s_mov_b32 s83, s80
	s_mov_b32 s81, s80
	v_mov_b64_e32 v[186:187], s[82:83]
	v_mov_b64_e32 v[184:185], s[80:81]
	ds_read_b128 v[160:163], v86 offset:4608
	ds_read_b128 v[164:167], v87 offset:4608
	v_mfma_f32_16x16x32_bf16 v[68:71], v[120:123], v[184:187], v[68:71]
	v_mfma_f32_16x16x32_bf16 v[56:59], v[124:127], v[184:187], v[56:59]
	v_mfma_f32_16x16x32_bf16 v[68:71], v[112:115], v[184:187], v[68:71]
	v_mfma_f32_16x16x32_bf16 v[56:59], v[116:119], v[184:187], v[56:59]
	s_waitcnt lgkmcnt(6)
	ds_read_b64_tr_b16 v[168:169], v214
	ds_read_b64_tr_b16 v[170:171], v214 offset:4096
	ds_read_b64_tr_b16 v[172:173], v214 offset:8192
	ds_read_b64_tr_b16 v[174:175], v214 offset:12288
	v_mfma_f32_16x16x32_bf16 v[84:87], v[128:131], v[240:243], v[72:75]
	v_mfma_f32_16x16x32_bf16 v[80:83], v[128:131], v[244:247], v[76:79]
	v_mfma_f32_16x16x32_bf16 v[84:87], v[132:135], v[152:155], v[84:87]
	v_mfma_f32_16x16x32_bf16 v[80:83], v[132:135], v[156:159], v[80:83]
	s_waitcnt lgkmcnt(8)
	ds_read_b64_tr_b16 v[176:177], v215
	ds_read_b64_tr_b16 v[178:179], v215 offset:4096
	ds_read_b64_tr_b16 v[180:181], v215 offset:8192
	ds_read_b64_tr_b16 v[182:183], v215 offset:12288
	v_mfma_f32_16x16x32_bf16 v[96:99], v[136:139], v[240:243], v[72:75]
	v_mfma_f32_16x16x32_bf16 v[88:91], v[136:139], v[244:247], v[76:79]
	v_mfma_f32_16x16x32_bf16 v[96:99], v[148:151], v[152:155], v[96:99]
	v_mfma_f32_16x16x32_bf16 v[88:91], v[148:151], v[156:159], v[88:91]
	s_waitcnt lgkmcnt(10)
	ds_read_b64_tr_b16 v[184:185], v214 offset:1024
	ds_read_b64_tr_b16 v[186:187], v214 offset:5120
	ds_read_b64_tr_b16 v[188:189], v214 offset:9216
	ds_read_b64_tr_b16 v[190:191], v214 offset:13312
	v_mfma_f32_16x16x32_bf16 v[100:103], v[140:143], v[240:243], v[72:75]
	v_mfma_f32_16x16x32_bf16 v[92:95], v[140:143], v[244:247], v[76:79]
	v_mfma_f32_16x16x32_bf16 v[100:103], v[144:147], v[152:155], v[100:103]
	v_mfma_f32_16x16x32_bf16 v[92:95], v[144:147], v[156:159], v[92:95]
	s_waitcnt lgkmcnt(12)
	v_mfma_f32_16x16x32_bf16 v[108:111], v[160:163], v[240:243], v[72:75]
	v_mfma_f32_16x16x32_bf16 v[104:107], v[160:163], v[244:247], v[76:79]
	v_mfma_f32_16x16x32_bf16 v[108:111], v[164:167], v[152:155], v[108:111]
	v_mfma_f32_16x16x32_bf16 v[104:107], v[164:167], v[156:159], v[104:107]
	s_cmp_lt_i32 s19, s75
	s_cbranch_scc0 .LBB0_411
.LBB0_403:
	s_waitcnt lgkmcnt(8)
	ds_read_b64_tr_b16 v[140:141], v215 offset:1024
	ds_read_b64_tr_b16 v[142:143], v215 offset:5120
	ds_read_b64_tr_b16 v[144:145], v215 offset:9216
	ds_read_b64_tr_b16 v[146:147], v215 offset:13312
	v_mfma_f32_16x16x32_bf16 v[60:63], v[120:123], v[168:171], v[60:63]
	v_max_i32_e32 v212, v84, v85
	v_max3_i32 v213, v87, v96, v97
	v_max3_i32 v212, v212, v86, v98
	v_max3_i32 v213, v213, v100, v101
	v_mfma_f32_16x16x32_bf16 v[64:67], v[124:127], v[168:171], v[64:67]
	v_max3_i32 v212, v212, v99, v102
	v_max3_i32 v213, v213, v108, v109
	v_max3_i32 v212, v212, v103, v110
	v_max3_i32 v242, v212, v111, v213
	v_mfma_f32_16x16x32_bf16 v[60:63], v[112:115], v[172:175], v[60:63]
	v_max_i32_e32 v212, v80, v81
	v_max3_i32 v213, v83, v88, v89
	v_max3_i32 v212, v212, v82, v90
	v_max3_i32 v213, v213, v92, v93
	v_mfma_f32_16x16x32_bf16 v[64:67], v[116:119], v[172:175], v[64:67]
	v_max3_i32 v212, v212, v91, v94
	v_max3_i32 v213, v213, v104, v105
	v_max3_i32 v212, v212, v95, v106
	v_max3_i32 v241, v212, v107, v213
	v_max_f32_e32 v240, v241, v241
	v_max_f32_e32 v243, v242, v242
	v_max_f32_e32 v212, v243, v240
	v_cmp_ge_f32_e32 vcc, s3, v212
	s_cmp_lg_u64 vcc, exec
	s_cselect_b64 s[6:7], -1, 0
	s_mov_b64 vcc, s[6:7]
	s_cbranch_vccnz .LBB0_415
	v_mov_b32_e32 v249, 1.0
	s_cbranch_execnz .LBB0_416

.LBB0_406:
	v_cmp_gt_i32_e32 vcc, s19, v235
	v_mov_b32_e32 v240, 0xf149f2ca
	v_cmp_gt_i32_e64 s[0:1], s19, v236
	v_cndmask_b32_e32 v84, v84, v240, vcc
	v_cndmask_b32_e32 v85, v85, v240, vcc
	v_cndmask_b32_e64 v80, v80, v240, s[0:1]
	v_cndmask_b32_e64 v81, v81, v240, s[0:1]
	v_cndmask_b32_e32 v86, v86, v240, vcc
	v_cndmask_b32_e64 v82, v82, v240, s[0:1]
	v_cndmask_b32_e32 v87, v87, v240, vcc
	v_cndmask_b32_e64 v83, v83, v240, s[0:1]
	v_cndmask_b32_e32 v96, v96, v240, vcc
	v_cndmask_b32_e64 v88, v88, v240, s[0:1]
	v_cndmask_b32_e32 v97, v97, v240, vcc
	v_cndmask_b32_e64 v89, v89, v240, s[0:1]
	v_cndmask_b32_e32 v98, v98, v240, vcc
	v_cndmask_b32_e64 v90, v90, v240, s[0:1]
	v_cndmask_b32_e32 v99, v99, v240, vcc
	v_cndmask_b32_e64 v91, v91, v240, s[0:1]
	v_cndmask_b32_e32 v100, v100, v240, vcc
	v_cndmask_b32_e64 v92, v92, v240, s[0:1]
	v_cndmask_b32_e32 v101, v101, v240, vcc
	v_cndmask_b32_e64 v93, v93, v240, s[0:1]
	v_cndmask_b32_e32 v102, v102, v240, vcc
	v_cndmask_b32_e64 v94, v94, v240, s[0:1]
	v_cndmask_b32_e32 v103, v103, v240, vcc
	v_cndmask_b32_e64 v95, v95, v240, s[0:1]
	v_cndmask_b32_e32 v108, v108, v240, vcc
	v_cndmask_b32_e64 v104, v104, v240, s[0:1]
	v_cndmask_b32_e32 v109, v109, v240, vcc
	v_cndmask_b32_e64 v105, v105, v240, s[0:1]
	v_cndmask_b32_e32 v110, v110, v240, vcc
	v_cndmask_b32_e64 v106, v106, v240, s[0:1]
	v_cndmask_b32_e32 v111, v111, v240, vcc
	v_cndmask_b32_e64 v107, v107, v240, s[0:1]
	s_branch .LBB0_398

.LBB0_411:
	v_cmp_lt_i32_e32 vcc, s19, v235
	v_mov_b32_e32 v160, 0xf149f2ca
	v_cmp_lt_i32_e64 s[0:1], s19, v236
	v_cndmask_b32_e32 v84, v160, v84, vcc
	v_cndmask_b32_e32 v85, v160, v85, vcc
	v_cndmask_b32_e64 v80, v160, v80, s[0:1]
	v_cndmask_b32_e64 v81, v160, v81, s[0:1]
	v_cndmask_b32_e32 v86, v160, v86, vcc
	v_cndmask_b32_e64 v82, v160, v82, s[0:1]
	v_cndmask_b32_e32 v87, v160, v87, vcc
	v_cndmask_b32_e64 v83, v160, v83, s[0:1]
	v_cndmask_b32_e32 v96, v160, v96, vcc
	v_cndmask_b32_e64 v88, v160, v88, s[0:1]
	v_cndmask_b32_e32 v97, v160, v97, vcc
	v_cndmask_b32_e64 v89, v160, v89, s[0:1]
	v_cndmask_b32_e32 v98, v160, v98, vcc
	v_cndmask_b32_e64 v90, v160, v90, s[0:1]
	v_cndmask_b32_e32 v99, v160, v99, vcc
	v_cndmask_b32_e64 v91, v160, v91, s[0:1]
	v_cndmask_b32_e32 v100, v160, v100, vcc
	v_cndmask_b32_e64 v92, v160, v92, s[0:1]
	v_cndmask_b32_e32 v101, v160, v101, vcc
	v_cndmask_b32_e64 v93, v160, v93, s[0:1]
	v_cndmask_b32_e32 v102, v160, v102, vcc
	v_cndmask_b32_e64 v94, v160, v94, s[0:1]
	v_cndmask_b32_e32 v103, v160, v103, vcc
	v_cndmask_b32_e64 v95, v160, v95, s[0:1]
	v_cndmask_b32_e32 v108, v160, v108, vcc
	v_cndmask_b32_e64 v104, v160, v104, s[0:1]
	v_cndmask_b32_e32 v109, v160, v109, vcc
	v_cndmask_b32_e64 v105, v160, v105, s[0:1]
	v_cndmask_b32_e32 v110, v160, v110, vcc
	v_cndmask_b32_e64 v106, v160, v106, s[0:1]
	v_cndmask_b32_e32 v111, v160, v111, vcc
	v_cndmask_b32_e64 v107, v160, v107, s[0:1]
	s_branch .LBB0_403

.LBB0_417:
	s_waitcnt lgkmcnt(8)
	ds_read_b64_tr_b16 v[160:161], v214 offset:2048
	ds_read_b64_tr_b16 v[162:163], v214 offset:6144
	ds_read_b64_tr_b16 v[164:165], v214 offset:10240
	ds_read_b64_tr_b16 v[166:167], v214 offset:14336
	v_mfma_f32_16x16x32_bf16 v[52:55], v[120:123], v[176:179], v[52:55]
	v_exp_f32_e32 v241, v84
	v_mfma_f32_16x16x32_bf16 v[48:51], v[124:127], v[176:179], v[48:51]
	v_exp_f32_e32 v244, v85
	v_mfma_f32_16x16x32_bf16 v[52:55], v[112:115], v[180:183], v[52:55]
	v_exp_f32_e32 v245, v86
	v_mfma_f32_16x16x32_bf16 v[48:51], v[116:119], v[180:183], v[48:51]
	v_exp_f32_e32 v247, v87
	v_exp_f32_e32 v240, v96
	s_waitcnt lgkmcnt(8)
	ds_read_b64_tr_b16 v[168:169], v215 offset:2048
	ds_read_b64_tr_b16 v[170:171], v215 offset:6144
	ds_read_b64_tr_b16 v[172:173], v215 offset:10240
	ds_read_b64_tr_b16 v[174:175], v215 offset:14336
	v_mfma_f32_16x16x32_bf16 v[44:47], v[120:123], v[184:187], v[44:47]
	v_exp_f32_e32 v242, v97
	v_mfma_f32_16x16x32_bf16 v[40:43], v[124:127], v[184:187], v[40:43]
	v_exp_f32_e32 v243, v98
	v_mfma_f32_16x16x32_bf16 v[44:47], v[112:115], v[188:191], v[44:47]
	v_exp_f32_e32 v246, v99
	v_mfma_f32_16x16x32_bf16 v[40:43], v[116:119], v[188:191], v[40:43]
	v_exp_f32_e32 v137, v80
	v_exp_f32_e32 v148, v81
	s_waitcnt lgkmcnt(8)
	ds_read_b64_tr_b16 v[176:177], v214 offset:3072
	ds_read_b64_tr_b16 v[178:179], v214 offset:7168
	ds_read_b64_tr_b16 v[180:181], v214 offset:11264
	ds_read_b64_tr_b16 v[182:183], v214 offset:15360
	v_mfma_f32_16x16x32_bf16 v[32:35], v[120:123], v[140:143], v[32:35]
	v_exp_f32_e32 v149, v82
	v_mfma_f32_16x16x32_bf16 v[36:39], v[124:127], v[140:143], v[36:39]
	v_exp_f32_e32 v151, v83
	v_mfma_f32_16x16x32_bf16 v[32:35], v[112:115], v[144:147], v[32:35]
	v_exp_f32_e32 v136, v89
	v_mfma_f32_16x16x32_bf16 v[36:39], v[116:119], v[144:147], v[36:39]
	v_exp_f32_e32 v139, v90
	v_exp_f32_e32 v150, v91
	s_waitcnt lgkmcnt(8)
	ds_read_b64_tr_b16 v[184:185], v215 offset:3072
	ds_read_b64_tr_b16 v[186:187], v215 offset:7168
	ds_read_b64_tr_b16 v[188:189], v215 offset:11264
	ds_read_b64_tr_b16 v[190:191], v215 offset:15360
	v_mfma_f32_16x16x32_bf16 v[20:23], v[120:123], v[160:163], v[20:23]
	v_exp_f32_e32 v129, v92
	v_mfma_f32_16x16x32_bf16 v[16:19], v[124:127], v[160:163], v[16:19]
	v_exp_f32_e32 v138, v95
	v_mfma_f32_16x16x32_bf16 v[20:23], v[112:115], v[164:167], v[20:23]
	v_exp_f32_e32 v128, v104
	v_mfma_f32_16x16x32_bf16 v[16:19], v[116:119], v[164:167], v[16:19]
	v_exp_f32_e32 v130, v105
	v_exp_f32_e32 v131, v106
	s_waitcnt lgkmcnt(8)
	v_mfma_f32_16x16x32_bf16 v[28:31], v[120:123], v[168:171], v[28:31]
	v_exp_f32_e32 v153, v100
	v_mfma_f32_16x16x32_bf16 v[24:27], v[124:127], v[168:171], v[24:27]
	v_exp_f32_e32 v152, v108
	v_mfma_f32_16x16x32_bf16 v[28:31], v[112:115], v[172:175], v[28:31]
	v_exp_f32_e32 v154, v109
	v_mfma_f32_16x16x32_bf16 v[24:27], v[116:119], v[172:175], v[24:27]
	v_exp_f32_e32 v155, v110
	s_waitcnt lgkmcnt(4)
	v_mfma_f32_16x16x32_bf16 v[12:15], v[120:123], v[176:179], v[12:15]
	v_exp_f32_e32 v156, v101
	v_mfma_f32_16x16x32_bf16 v[8:11], v[124:127], v[176:179], v[8:11]
	v_exp_f32_e32 v158, v102
	v_mfma_f32_16x16x32_bf16 v[12:15], v[112:115], v[180:183], v[12:15]
	v_exp_f32_e32 v159, v103
	v_mfma_f32_16x16x32_bf16 v[8:11], v[116:119], v[180:183], v[8:11]
	v_exp_f32_e32 v157, v111
	s_waitcnt lgkmcnt(0)
	v_mfma_f32_16x16x32_bf16 v[4:7], v[120:123], v[184:187], v[4:7]
	v_exp_f32_e32 v132, v88
	v_mfma_f32_16x16x32_bf16 v[0:3], v[124:127], v[184:187], v[0:3]
	v_exp_f32_e32 v134, v93
	v_mfma_f32_16x16x32_bf16 v[4:7], v[112:115], v[188:191], v[4:7]
	v_exp_f32_e32 v135, v94
	v_mfma_f32_16x16x32_bf16 v[0:3], v[116:119], v[188:191], v[0:3]
	v_exp_f32_e32 v133, v107
	s_waitcnt vmcnt(3)
	s_waitcnt lgkmcnt(0)
	s_add_i32 s15, s15, 0x8000
	s_addk_i32 s16, 0x4000
	s_cmp_ge_i32 s17, s14
	s_cselect_b64 s[0:1], -1, 0
	s_barrier
	s_and_b64 vcc, exec, s[0:1]
	s_mov_b32 s19, s17
	s_cbranch_vccz .LBB0_396
	s_branch .LBB0_419
